# first-layer H1 epilogue stores write-through (sc1); the publish step drops its L2 write-back before the counter update
# baseline (speedup 1.0000x reference)
; __device__ __forceinline__ float gelu_tanh(float x) { return x * sigm(1.5957691216f * (x + 0.044715f * x * x * x)); }
; __device__ __forceinline__ u32x4 pack8(f32x4 a, f32x4 b) { u32x4 o; o.x = pk2(a[0], a[1]); o.y = pk2(a[2], a[3]); o.z = pk2(b[0], b[1]); o.w = pk2(b[2], b[3]); return o; }
;     __device__ __forceinline__ void operator()(AccRef acc, const Unit& u, int wr, int wc, int fr, int fq) const {
;         const int row0 = u.pm * 256 + wr * 64 + fr, col0 = wc * 32 + 8 * fq;
; #pragma unroll
;         for (int bj = 0; bj < 2; ++bj) { const f32x4 b0 = *(const f32x4*)(bias + col0 + bj * 128), b1 = *(const f32x4*)(bias + col0 + bj * 128 + 4);
; #pragma unroll
;             for (int ai = 0; ai < 2; ++ai)
; #pragma unroll
;                 for (int m = 0; m < 4; ++m) { f32x4 a, b;
; #pragma unroll
;                     for (int i = 0; i < 4; ++i) { a[i] = gelu_tanh(acc[ai][bj][m][0][i] + b0[i]); b[i] = gelu_tanh(acc[ai][bj][m][1][i] + b1[i]); }
;                     *(u32x4*)(O + (size_t)(row0 + ai * 128 + m * 16) * 256 + col0 + bj * 128) = pack8(a, b); } }
.LBB0_538:
	global_load_dwordx4 v[96:99], v[144:145], off offset:16
	global_load_dwordx4 v[100:103], v[144:145], off
	v_lshl_add_u32 v152, s56, 8, v155
	s_mov_b64 s[10:11], 0x10000
	s_mov_b64 s[14:15], -1
	s_waitcnt vmcnt(0)
	v_add_f32_e32 v128, v128, v96
	v_add_f32_e32 v132, v132, v100
	v_mul_f32_e32 v153, 0x3d372713, v132
	v_mul_f32_e32 v153, v132, v153
	v_fma_f32 v153, v132, v153, v132
	v_mul_f32_e32 v153, 0x3fcc422a, v153
	v_mul_f32_e32 v153, 0xbfb8aa3b, v153
	v_exp_f32_e32 v153, v153
	v_add_f32_e32 v129, v129, v97
	v_add_f32_e32 v130, v130, v98
	v_add_f32_e32 v131, v131, v99
	v_add_f32_e32 v153, 1.0, v153
	v_rcp_f32_e32 v153, v153
	v_add_f32_e32 v124, v124, v100
	v_add_f32_e32 v120, v120, v96
	v_add_f32_e32 v125, v125, v101
	v_mul_f32_e32 v132, v132, v153
	v_mul_f32_e32 v153, 0x3d372713, v128
	v_mul_f32_e32 v153, v128, v153
	v_fma_f32 v153, v128, v153, v128
	v_mul_f32_e32 v153, 0x3fcc422a, v153
	v_mul_f32_e32 v153, 0xbfb8aa3b, v153
	v_exp_f32_e32 v153, v153
	v_add_f32_e32 v121, v121, v97
	v_add_f32_e32 v126, v126, v102
	v_add_f32_e32 v122, v122, v98
	v_add_f32_e32 v153, 1.0, v153
	v_rcp_f32_e32 v153, v153
	v_add_f32_e32 v116, v116, v100
	v_add_f32_e32 v112, v112, v96
	v_add_f32_e32 v117, v117, v101
	v_mul_f32_e32 v153, v128, v153
	v_add_f32_e32 v128, v133, v101
	v_mul_f32_e32 v133, 0x3d372713, v128
	v_mul_f32_e32 v133, v128, v133
	v_fma_f32 v133, v128, v133, v128
	v_mul_f32_e32 v133, 0x3fcc422a, v133
	v_mul_f32_e32 v133, 0xbfb8aa3b, v133
	v_exp_f32_e32 v133, v133
	v_add_f32_e32 v113, v113, v97
	v_add_f32_e32 v118, v118, v102
	v_add_f32_e32 v114, v114, v98
	v_add_f32_e32 v133, 1.0, v133
	v_rcp_f32_e32 v133, v133
	v_add_f32_e32 v108, v108, v100
	v_add_f32_e32 v104, v104, v96
	v_add_f32_e32 v109, v109, v101
	v_mul_f32_e32 v128, v128, v133
	v_mul_f32_e32 v133, 0x3d372713, v129
	v_mul_f32_e32 v133, v129, v133
	v_fma_f32 v133, v129, v133, v129
	v_mul_f32_e32 v133, 0x3fcc422a, v133
	v_mul_f32_e32 v133, 0xbfb8aa3b, v133
	v_exp_f32_e32 v133, v133
	v_cvt_pk_bf16_f32 v128, v132, v128
	v_add_f32_e32 v105, v105, v97
	v_add_f32_e32 v110, v110, v102
	v_add_f32_e32 v133, 1.0, v133
	v_rcp_f32_e32 v133, v133
	v_add_f32_e32 v106, v106, v98
	v_add_f32_e32 v92, v92, v100
	v_add_f32_e32 v88, v88, v96
	v_mul_f32_e32 v133, v129, v133
	v_add_f32_e32 v129, v134, v102
	v_mul_f32_e32 v134, 0x3d372713, v129
	v_mul_f32_e32 v134, v129, v134
	v_fma_f32 v134, v129, v134, v129
	v_mul_f32_e32 v134, 0x3fcc422a, v134
	v_mul_f32_e32 v134, 0xbfb8aa3b, v134
	v_exp_f32_e32 v134, v134
	v_add_f32_e32 v93, v93, v101
	v_add_f32_e32 v89, v89, v97
	v_add_f32_e32 v94, v94, v102
	v_add_f32_e32 v134, 1.0, v134
	v_rcp_f32_e32 v134, v134
	v_add_f32_e32 v90, v90, v98
	v_add_f32_e32 v84, v84, v100
	v_add_f32_e32 v80, v80, v96
	v_mul_f32_e32 v129, v129, v134
	v_mul_f32_e32 v134, 0x3d372713, v130
	v_mul_f32_e32 v134, v130, v134
	v_fma_f32 v134, v130, v134, v130
	v_mul_f32_e32 v134, 0x3fcc422a, v134
	v_mul_f32_e32 v134, 0xbfb8aa3b, v134
	v_exp_f32_e32 v134, v134
	v_add_f32_e32 v85, v85, v101
	v_add_f32_e32 v81, v81, v97
	v_add_f32_e32 v86, v86, v102
	v_add_f32_e32 v134, 1.0, v134
	v_rcp_f32_e32 v134, v134
	v_add_f32_e32 v82, v82, v98
	v_add_f32_e32 v76, v76, v100
	v_add_f32_e32 v72, v72, v96
	v_mul_f32_e32 v134, v130, v134
	v_add_f32_e32 v130, v135, v103
	v_mul_f32_e32 v135, 0x3d372713, v130
	v_mul_f32_e32 v135, v130, v135
	v_fma_f32 v135, v130, v135, v130
	v_mul_f32_e32 v135, 0x3fcc422a, v135
	v_mul_f32_e32 v135, 0xbfb8aa3b, v135
	v_exp_f32_e32 v135, v135
	v_add_f32_e32 v77, v77, v101
	v_add_f32_e32 v73, v73, v97
	v_add_f32_e32 v78, v78, v102
	v_add_f32_e32 v135, 1.0, v135
	v_rcp_f32_e32 v135, v135
	v_add_f32_e32 v74, v74, v98
	v_add_f32_e32 v68, v68, v100
	v_add_f32_e32 v64, v64, v96
	v_mul_f32_e32 v130, v130, v135
	v_mul_f32_e32 v135, 0x3d372713, v131
	v_mul_f32_e32 v135, v131, v135
	v_fma_f32 v135, v131, v135, v131
	v_mul_f32_e32 v135, 0x3fcc422a, v135
	v_mul_f32_e32 v135, 0xbfb8aa3b, v135
	v_exp_f32_e32 v135, v135
	v_cvt_pk_bf16_f32 v129, v129, v130
	v_cvt_pk_bf16_f32 v130, v153, v133
	v_ashrrev_i32_e32 v153, 31, v152
	v_add_f32_e32 v135, 1.0, v135
	v_rcp_f32_e32 v135, v135
	v_lshlrev_b64 v[132:133], 9, v[152:153]
	v_lshl_add_u64 v[132:133], v[146:147], 0, v[132:133]
	v_add_f32_e32 v65, v65, v97
	v_mul_f32_e32 v131, v131, v135
	v_cvt_pk_bf16_f32 v131, v134, v131
	global_store_dwordx4 v[132:133], v[128:131], off sc1
	v_add_f32_e32 v66, v66, v98
	v_add_f32_e32 v67, v67, v99
	v_mul_f32_e32 v128, 0x3d372713, v124
	v_mul_f32_e32 v128, v124, v128
	v_fma_f32 v128, v124, v128, v124
	v_mul_f32_e32 v128, 0x3fcc422a, v128
	v_mul_f32_e32 v128, 0xbfb8aa3b, v128
	v_exp_f32_e32 v128, v128
	s_nop 0
	v_add_f32_e32 v128, 1.0, v128
	v_rcp_f32_e32 v128, v128
	s_nop 0
	v_mul_f32_e32 v124, v124, v128
	v_mul_f32_e32 v128, 0x3d372713, v120
	v_mul_f32_e32 v128, v120, v128
	v_fma_f32 v128, v120, v128, v120
	v_mul_f32_e32 v128, 0x3fcc422a, v128
	v_mul_f32_e32 v128, 0xbfb8aa3b, v128
	v_exp_f32_e32 v128, v128
	s_nop 0
	v_add_f32_e32 v128, 1.0, v128
	v_rcp_f32_e32 v128, v128
	s_nop 0
	v_mul_f32_e32 v120, v120, v128
	v_mul_f32_e32 v128, 0x3d372713, v125
	v_mul_f32_e32 v128, v125, v128
	v_fma_f32 v128, v125, v128, v125
	v_mul_f32_e32 v128, 0x3fcc422a, v128
	v_mul_f32_e32 v128, 0xbfb8aa3b, v128
	v_exp_f32_e32 v128, v128
	s_nop 0
	v_add_f32_e32 v128, 1.0, v128
	v_rcp_f32_e32 v128, v128
	s_nop 0
	v_mul_f32_e32 v125, v125, v128
	v_mul_f32_e32 v128, 0x3d372713, v121
	v_mul_f32_e32 v128, v121, v128
	v_fma_f32 v128, v121, v128, v121
	v_mul_f32_e32 v128, 0x3fcc422a, v128
	v_mul_f32_e32 v128, 0xbfb8aa3b, v128
	v_exp_f32_e32 v128, v128
	s_nop 0
	v_add_f32_e32 v128, 1.0, v128
	v_rcp_f32_e32 v128, v128
	s_nop 0
; __device__ __forceinline__ float gelu_tanh(float x) { return x * sigm(1.5957691216f * (x + 0.044715f * x * x * x)); }
; __device__ __forceinline__ u32x4 pack8(f32x4 a, f32x4 b) { u32x4 o; o.x = pk2(a[0], a[1]); o.y = pk2(a[2], a[3]); o.z = pk2(b[0], b[1]); o.w = pk2(b[2], b[3]); return o; }
;     __device__ __forceinline__ void operator()(AccRef acc, const Unit& u, int wr, int wc, int fr, int fq) const {
;         const int row0 = u.pm * 256 + wr * 64 + fr, col0 = wc * 32 + 8 * fq;
; #pragma unroll
;         for (int bj = 0; bj < 2; ++bj) { const f32x4 b0 = *(const f32x4*)(bias + col0 + bj * 128), b1 = *(const f32x4*)(bias + col0 + bj * 128 + 4);
; #pragma unroll
;             for (int ai = 0; ai < 2; ++ai)
; #pragma unroll
;                 for (int m = 0; m < 4; ++m) { f32x4 a, b;
; #pragma unroll
;                     for (int i = 0; i < 4; ++i) { a[i] = gelu_tanh(acc[ai][bj][m][0][i] + b0[i]); b[i] = gelu_tanh(acc[ai][bj][m][1][i] + b1[i]); }
;                     *(u32x4*)(O + (size_t)(row0 + ai * 128 + m * 16) * 256 + col0 + bj * 128) = pack8(a, b); } }
	v_mul_f32_e32 v121, v121, v128
	v_mul_f32_e32 v128, 0x3d372713, v126
	v_mul_f32_e32 v128, v126, v128
	v_fma_f32 v128, v126, v128, v126
	v_mul_f32_e32 v128, 0x3fcc422a, v128
	v_mul_f32_e32 v128, 0xbfb8aa3b, v128
	v_exp_f32_e32 v128, v128
	s_nop 0
	v_add_f32_e32 v128, 1.0, v128
	v_rcp_f32_e32 v128, v128
	s_nop 0
	v_mul_f32_e32 v126, v126, v128
	v_mul_f32_e32 v128, 0x3d372713, v122
	v_mul_f32_e32 v128, v122, v128
	v_fma_f32 v128, v122, v128, v122
	v_mul_f32_e32 v128, 0x3fcc422a, v128
	v_mul_f32_e32 v128, 0xbfb8aa3b, v128
	v_exp_f32_e32 v128, v128
	s_nop 0
	v_add_f32_e32 v128, 1.0, v128
	v_rcp_f32_e32 v128, v128
	s_nop 0
	v_mul_f32_e32 v128, v122, v128
	v_add_f32_e32 v122, v127, v103
	v_mul_f32_e32 v127, 0x3d372713, v122
	v_mul_f32_e32 v127, v122, v127
	v_fma_f32 v127, v122, v127, v122
	v_mul_f32_e32 v127, 0x3fcc422a, v127
	v_mul_f32_e32 v127, 0xbfb8aa3b, v127
	v_exp_f32_e32 v127, v127
	s_nop 0
	v_add_f32_e32 v127, 1.0, v127
	v_rcp_f32_e32 v127, v127
	s_nop 0
	v_mul_f32_e32 v127, v122, v127
	v_add_f32_e32 v122, v123, v99
	v_mul_f32_e32 v123, 0x3d372713, v122
	v_mul_f32_e32 v123, v122, v123
	v_fma_f32 v123, v122, v123, v122
	v_mul_f32_e32 v123, 0x3fcc422a, v123
	v_mul_f32_e32 v123, 0xbfb8aa3b, v123
	v_exp_f32_e32 v123, v123
	s_nop 0
	v_add_f32_e32 v123, 1.0, v123
	v_rcp_f32_e32 v123, v123
	s_nop 0
	v_mul_f32_e32 v129, v122, v123
	v_cvt_pk_bf16_f32 v122, v124, v125
	v_cvt_pk_bf16_f32 v123, v126, v127
	v_cvt_pk_bf16_f32 v124, v120, v121
	v_or_b32_e32 v120, 16, v152
	v_ashrrev_i32_e32 v121, 31, v120
	v_lshlrev_b64 v[120:121], 9, v[120:121]
	v_lshl_add_u64 v[120:121], v[146:147], 0, v[120:121]
	v_cvt_pk_bf16_f32 v125, v128, v129
	global_store_dwordx4 v[120:121], v[122:125], off sc1
	s_nop 1
	v_mul_f32_e32 v122, 0x3d372713, v116
	v_mul_f32_e32 v122, v116, v122
	v_fma_f32 v122, v116, v122, v116
	v_mul_f32_e32 v122, 0x3fcc422a, v122
	v_mul_f32_e32 v122, 0xbfb8aa3b, v122
	v_exp_f32_e32 v122, v122
	s_nop 0
	v_add_f32_e32 v122, 1.0, v122
	v_rcp_f32_e32 v122, v122
	s_nop 0
	v_mul_f32_e32 v116, v116, v122
	v_mul_f32_e32 v122, 0x3d372713, v112
	v_mul_f32_e32 v122, v112, v122
	v_fma_f32 v122, v112, v122, v112
	v_mul_f32_e32 v122, 0x3fcc422a, v122
	v_mul_f32_e32 v122, 0xbfb8aa3b, v122
	v_exp_f32_e32 v122, v122
	s_nop 0
	v_add_f32_e32 v122, 1.0, v122
	v_rcp_f32_e32 v122, v122
	s_nop 0
	v_mul_f32_e32 v112, v112, v122
	v_mul_f32_e32 v122, 0x3d372713, v117
	v_mul_f32_e32 v122, v117, v122
	v_fma_f32 v122, v117, v122, v117
	v_mul_f32_e32 v122, 0x3fcc422a, v122
	v_mul_f32_e32 v122, 0xbfb8aa3b, v122
	v_exp_f32_e32 v122, v122
	s_nop 0
	v_add_f32_e32 v122, 1.0, v122
	v_rcp_f32_e32 v122, v122
	s_nop 0
	v_mul_f32_e32 v117, v117, v122
	v_mul_f32_e32 v122, 0x3d372713, v113
	v_mul_f32_e32 v122, v113, v122
	v_fma_f32 v122, v113, v122, v113
	v_mul_f32_e32 v122, 0x3fcc422a, v122
	v_mul_f32_e32 v122, 0xbfb8aa3b, v122
	v_exp_f32_e32 v122, v122
	s_nop 0
	v_add_f32_e32 v122, 1.0, v122
	v_rcp_f32_e32 v122, v122
	s_nop 0
	v_mul_f32_e32 v113, v113, v122
	v_mul_f32_e32 v122, 0x3d372713, v118
	v_mul_f32_e32 v122, v118, v122
	v_fma_f32 v122, v118, v122, v118
	v_mul_f32_e32 v122, 0x3fcc422a, v122
	v_mul_f32_e32 v122, 0xbfb8aa3b, v122
	v_exp_f32_e32 v122, v122
	s_nop 0
	v_add_f32_e32 v122, 1.0, v122
	v_rcp_f32_e32 v122, v122
	s_nop 0
	v_mul_f32_e32 v118, v118, v122
	v_mul_f32_e32 v122, 0x3d372713, v114
	v_mul_f32_e32 v122, v114, v122
	v_fma_f32 v122, v114, v122, v114
	v_mul_f32_e32 v122, 0x3fcc422a, v122
	v_mul_f32_e32 v122, 0xbfb8aa3b, v122
	v_exp_f32_e32 v122, v122
	s_nop 0
	v_add_f32_e32 v122, 1.0, v122
	v_rcp_f32_e32 v122, v122
	s_nop 0
	v_mul_f32_e32 v122, v114, v122
	v_add_f32_e32 v114, v119, v103
	v_mul_f32_e32 v119, 0x3d372713, v114
	v_mul_f32_e32 v119, v114, v119
	v_fma_f32 v119, v114, v119, v114
	v_mul_f32_e32 v119, 0x3fcc422a, v119
	v_mul_f32_e32 v119, 0xbfb8aa3b, v119
	v_exp_f32_e32 v119, v119
	s_nop 0
	v_add_f32_e32 v119, 1.0, v119
	v_rcp_f32_e32 v119, v119
	s_nop 0
	v_mul_f32_e32 v119, v114, v119
	v_add_f32_e32 v114, v115, v99
	v_mul_f32_e32 v115, 0x3d372713, v114
	v_mul_f32_e32 v115, v114, v115
	v_fma_f32 v115, v114, v115, v114
	v_mul_f32_e32 v115, 0x3fcc422a, v115
	v_mul_f32_e32 v115, 0xbfb8aa3b, v115
	v_exp_f32_e32 v115, v115
	s_nop 0
	v_add_f32_e32 v115, 1.0, v115
	v_rcp_f32_e32 v115, v115
	s_nop 0
	v_mul_f32_e32 v123, v114, v115
	v_cvt_pk_bf16_f32 v114, v116, v117
	v_cvt_pk_bf16_f32 v115, v118, v119
	v_cvt_pk_bf16_f32 v116, v112, v113
	v_or_b32_e32 v112, 32, v152
	v_ashrrev_i32_e32 v113, 31, v112
	v_lshlrev_b64 v[112:113], 9, v[112:113]
	v_lshl_add_u64 v[112:113], v[146:147], 0, v[112:113]
	v_cvt_pk_bf16_f32 v117, v122, v123
	global_store_dwordx4 v[112:113], v[114:117], off sc1
	s_nop 1
	v_mul_f32_e32 v114, 0x3d372713, v108
	v_mul_f32_e32 v114, v108, v114
	v_fma_f32 v114, v108, v114, v108
	v_mul_f32_e32 v114, 0x3fcc422a, v114
	v_mul_f32_e32 v114, 0xbfb8aa3b, v114
	v_exp_f32_e32 v114, v114
	s_nop 0
	v_add_f32_e32 v114, 1.0, v114
	v_rcp_f32_e32 v114, v114
	s_nop 0
	v_mul_f32_e32 v108, v108, v114
	v_mul_f32_e32 v114, 0x3d372713, v104
	v_mul_f32_e32 v114, v104, v114
	v_fma_f32 v114, v104, v114, v104
	v_mul_f32_e32 v114, 0x3fcc422a, v114
	v_mul_f32_e32 v114, 0xbfb8aa3b, v114
	v_exp_f32_e32 v114, v114
	s_nop 0
	v_add_f32_e32 v114, 1.0, v114
	v_rcp_f32_e32 v114, v114
	s_nop 0
	v_mul_f32_e32 v104, v104, v114
	v_mul_f32_e32 v114, 0x3d372713, v109
	v_mul_f32_e32 v114, v109, v114
	v_fma_f32 v114, v109, v114, v109
	v_mul_f32_e32 v114, 0x3fcc422a, v114
	v_mul_f32_e32 v114, 0xbfb8aa3b, v114
	v_exp_f32_e32 v114, v114
	s_nop 0
	v_add_f32_e32 v114, 1.0, v114
	v_rcp_f32_e32 v114, v114
	s_nop 0
	v_mul_f32_e32 v109, v109, v114
	v_mul_f32_e32 v114, 0x3d372713, v105
	v_mul_f32_e32 v114, v105, v114
; __device__ __forceinline__ float gelu_tanh(float x) { return x * sigm(1.5957691216f * (x + 0.044715f * x * x * x)); }
; __device__ __forceinline__ u32x4 pack8(f32x4 a, f32x4 b) { u32x4 o; o.x = pk2(a[0], a[1]); o.y = pk2(a[2], a[3]); o.z = pk2(b[0], b[1]); o.w = pk2(b[2], b[3]); return o; }
;     __device__ __forceinline__ void operator()(AccRef acc, const Unit& u, int wr, int wc, int fr, int fq) const {
;         const int row0 = u.pm * 256 + wr * 64 + fr, col0 = wc * 32 + 8 * fq;
; #pragma unroll
;         for (int bj = 0; bj < 2; ++bj) { const f32x4 b0 = *(const f32x4*)(bias + col0 + bj * 128), b1 = *(const f32x4*)(bias + col0 + bj * 128 + 4);
; #pragma unroll
;             for (int ai = 0; ai < 2; ++ai)
; #pragma unroll
;                 for (int m = 0; m < 4; ++m) { f32x4 a, b;
; #pragma unroll
;                     for (int i = 0; i < 4; ++i) { a[i] = gelu_tanh(acc[ai][bj][m][0][i] + b0[i]); b[i] = gelu_tanh(acc[ai][bj][m][1][i] + b1[i]); }
;                     *(u32x4*)(O + (size_t)(row0 + ai * 128 + m * 16) * 256 + col0 + bj * 128) = pack8(a, b); } }
	v_fma_f32 v114, v105, v114, v105
	v_mul_f32_e32 v114, 0x3fcc422a, v114
	v_mul_f32_e32 v114, 0xbfb8aa3b, v114
	v_exp_f32_e32 v114, v114
	s_nop 0
	v_add_f32_e32 v114, 1.0, v114
	v_rcp_f32_e32 v114, v114
	s_nop 0
	v_mul_f32_e32 v105, v105, v114
	v_mul_f32_e32 v114, 0x3d372713, v110
	v_mul_f32_e32 v114, v110, v114
	v_fma_f32 v114, v110, v114, v110
	v_mul_f32_e32 v114, 0x3fcc422a, v114
	v_mul_f32_e32 v114, 0xbfb8aa3b, v114
	v_exp_f32_e32 v114, v114
	s_nop 0
	v_add_f32_e32 v114, 1.0, v114
	v_rcp_f32_e32 v114, v114
	s_nop 0
	v_mul_f32_e32 v110, v110, v114
	v_mul_f32_e32 v114, 0x3d372713, v106
	v_mul_f32_e32 v114, v106, v114
	v_fma_f32 v114, v106, v114, v106
	v_mul_f32_e32 v114, 0x3fcc422a, v114
	v_mul_f32_e32 v114, 0xbfb8aa3b, v114
	v_exp_f32_e32 v114, v114
	s_nop 0
	v_add_f32_e32 v114, 1.0, v114
	v_rcp_f32_e32 v114, v114
	s_nop 0
	v_mul_f32_e32 v114, v106, v114
	v_add_f32_e32 v106, v111, v103
	v_mul_f32_e32 v111, 0x3d372713, v106
	v_mul_f32_e32 v111, v106, v111
	v_fma_f32 v111, v106, v111, v106
	v_mul_f32_e32 v111, 0x3fcc422a, v111
	v_mul_f32_e32 v111, 0xbfb8aa3b, v111
	v_exp_f32_e32 v111, v111
	s_nop 0
	v_add_f32_e32 v111, 1.0, v111
	v_rcp_f32_e32 v111, v111
	s_nop 0
	v_mul_f32_e32 v111, v106, v111
	v_add_f32_e32 v106, v107, v99
	v_mul_f32_e32 v107, 0x3d372713, v106
	v_mul_f32_e32 v107, v106, v107
	v_fma_f32 v107, v106, v107, v106
	v_mul_f32_e32 v107, 0x3fcc422a, v107
	v_mul_f32_e32 v107, 0xbfb8aa3b, v107
	v_exp_f32_e32 v107, v107
	s_nop 0
	v_add_f32_e32 v107, 1.0, v107
	v_rcp_f32_e32 v107, v107
	s_nop 0
	v_mul_f32_e32 v115, v106, v107
	v_cvt_pk_bf16_f32 v106, v108, v109
	v_cvt_pk_bf16_f32 v107, v110, v111
	v_cvt_pk_bf16_f32 v108, v104, v105
	v_or_b32_e32 v104, 48, v152
	v_ashrrev_i32_e32 v105, 31, v104
	v_lshlrev_b64 v[104:105], 9, v[104:105]
	v_lshl_add_u64 v[104:105], v[146:147], 0, v[104:105]
	v_cvt_pk_bf16_f32 v109, v114, v115
	global_store_dwordx4 v[104:105], v[106:109], off sc1
	s_nop 1
	v_mul_f32_e32 v106, 0x3d372713, v92
	v_mul_f32_e32 v106, v92, v106
	v_fma_f32 v106, v92, v106, v92
	v_mul_f32_e32 v106, 0x3fcc422a, v106
	v_mul_f32_e32 v106, 0xbfb8aa3b, v106
	v_exp_f32_e32 v106, v106
	s_nop 0
	v_add_f32_e32 v106, 1.0, v106
	v_rcp_f32_e32 v106, v106
	s_nop 0
	v_mul_f32_e32 v92, v92, v106
	v_mul_f32_e32 v106, 0x3d372713, v88
	v_mul_f32_e32 v106, v88, v106
	v_fma_f32 v106, v88, v106, v88
	v_mul_f32_e32 v106, 0x3fcc422a, v106
	v_mul_f32_e32 v106, 0xbfb8aa3b, v106
	v_exp_f32_e32 v106, v106
	s_nop 0
	v_add_f32_e32 v106, 1.0, v106
	v_rcp_f32_e32 v106, v106
	s_nop 0
	v_mul_f32_e32 v88, v88, v106
	v_mul_f32_e32 v106, 0x3d372713, v93
	v_mul_f32_e32 v106, v93, v106
	v_fma_f32 v106, v93, v106, v93
	v_mul_f32_e32 v106, 0x3fcc422a, v106
	v_mul_f32_e32 v106, 0xbfb8aa3b, v106
	v_exp_f32_e32 v106, v106
	s_nop 0
	v_add_f32_e32 v106, 1.0, v106
	v_rcp_f32_e32 v106, v106
	s_nop 0
	v_mul_f32_e32 v93, v93, v106
	v_mul_f32_e32 v106, 0x3d372713, v89
	v_mul_f32_e32 v106, v89, v106
	v_fma_f32 v106, v89, v106, v89
	v_mul_f32_e32 v106, 0x3fcc422a, v106
	v_mul_f32_e32 v106, 0xbfb8aa3b, v106
	v_exp_f32_e32 v106, v106
	s_nop 0
	v_add_f32_e32 v106, 1.0, v106
	v_rcp_f32_e32 v106, v106
	s_nop 0
	v_mul_f32_e32 v89, v89, v106
	v_mul_f32_e32 v106, 0x3d372713, v94
	v_mul_f32_e32 v106, v94, v106
	v_fma_f32 v106, v94, v106, v94
	v_mul_f32_e32 v106, 0x3fcc422a, v106
	v_mul_f32_e32 v106, 0xbfb8aa3b, v106
	v_exp_f32_e32 v106, v106
	s_nop 0
	v_add_f32_e32 v106, 1.0, v106
	v_rcp_f32_e32 v106, v106
	s_nop 0
	v_mul_f32_e32 v94, v94, v106
	v_mul_f32_e32 v106, 0x3d372713, v90
	v_mul_f32_e32 v106, v90, v106
	v_fma_f32 v106, v90, v106, v90
	v_mul_f32_e32 v106, 0x3fcc422a, v106
	v_mul_f32_e32 v106, 0xbfb8aa3b, v106
	v_exp_f32_e32 v106, v106
	s_nop 0
	v_add_f32_e32 v106, 1.0, v106
	v_rcp_f32_e32 v106, v106
	s_nop 0
	v_mul_f32_e32 v106, v90, v106
	v_add_f32_e32 v90, v95, v103
	v_mul_f32_e32 v95, 0x3d372713, v90
	v_mul_f32_e32 v95, v90, v95
	v_fma_f32 v95, v90, v95, v90
	v_mul_f32_e32 v95, 0x3fcc422a, v95
	v_mul_f32_e32 v95, 0xbfb8aa3b, v95
	v_exp_f32_e32 v95, v95
	s_nop 0
	v_add_f32_e32 v95, 1.0, v95
	v_rcp_f32_e32 v95, v95
	s_nop 0
	v_mul_f32_e32 v95, v90, v95
	v_add_f32_e32 v90, v91, v99
	v_mul_f32_e32 v91, 0x3d372713, v90
	v_mul_f32_e32 v91, v90, v91
	v_fma_f32 v91, v90, v91, v90
	v_mul_f32_e32 v91, 0x3fcc422a, v91
	v_mul_f32_e32 v91, 0xbfb8aa3b, v91
	v_exp_f32_e32 v91, v91
	s_nop 0
	v_add_f32_e32 v91, 1.0, v91
	v_rcp_f32_e32 v91, v91
	s_nop 0
	v_mul_f32_e32 v107, v90, v91
	v_cvt_pk_bf16_f32 v90, v92, v93
	v_cvt_pk_bf16_f32 v91, v94, v95
	v_cvt_pk_bf16_f32 v92, v88, v89
	v_lshl_add_u64 v[88:89], v[132:133], 0, s[10:11]
	s_mov_b32 s10, 0x10000
	v_add_co_u32_e32 v94, vcc, s10, v132
	v_cvt_pk_bf16_f32 v93, v106, v107
	s_mov_b64 s[10:11], 0x12000
	s_nop 0
	v_addc_co_u32_e32 v95, vcc, 0, v133, vcc
	global_store_dwordx4 v[94:95], v[90:93], off sc1
	s_nop 1
	v_mul_f32_e32 v90, 0x3d372713, v84
	v_mul_f32_e32 v90, v84, v90
	v_fma_f32 v90, v84, v90, v84
	v_mul_f32_e32 v90, 0x3fcc422a, v90
	v_mul_f32_e32 v90, 0xbfb8aa3b, v90
	v_exp_f32_e32 v90, v90
	s_nop 0
	v_add_f32_e32 v90, 1.0, v90
	v_rcp_f32_e32 v90, v90
	s_nop 0
	v_mul_f32_e32 v84, v84, v90
	v_mul_f32_e32 v90, 0x3d372713, v80
	v_mul_f32_e32 v90, v80, v90
	v_fma_f32 v90, v80, v90, v80
	v_mul_f32_e32 v90, 0x3fcc422a, v90
	v_mul_f32_e32 v90, 0xbfb8aa3b, v90
	v_exp_f32_e32 v90, v90
	s_nop 0
	v_add_f32_e32 v90, 1.0, v90
	v_rcp_f32_e32 v90, v90
	s_nop 0
	v_mul_f32_e32 v80, v80, v90
	v_mul_f32_e32 v90, 0x3d372713, v85
	v_mul_f32_e32 v90, v85, v90
	v_fma_f32 v90, v85, v90, v85
	v_mul_f32_e32 v90, 0x3fcc422a, v90
	v_mul_f32_e32 v90, 0xbfb8aa3b, v90
	v_exp_f32_e32 v90, v90
	s_nop 0
	v_add_f32_e32 v90, 1.0, v90
	v_rcp_f32_e32 v90, v90
	s_nop 0
; __device__ __forceinline__ float gelu_tanh(float x) { return x * sigm(1.5957691216f * (x + 0.044715f * x * x * x)); }
; __device__ __forceinline__ u32x4 pack8(f32x4 a, f32x4 b) { u32x4 o; o.x = pk2(a[0], a[1]); o.y = pk2(a[2], a[3]); o.z = pk2(b[0], b[1]); o.w = pk2(b[2], b[3]); return o; }
;     __device__ __forceinline__ void operator()(AccRef acc, const Unit& u, int wr, int wc, int fr, int fq) const {
;         const int row0 = u.pm * 256 + wr * 64 + fr, col0 = wc * 32 + 8 * fq;
; #pragma unroll
;         for (int bj = 0; bj < 2; ++bj) { const f32x4 b0 = *(const f32x4*)(bias + col0 + bj * 128), b1 = *(const f32x4*)(bias + col0 + bj * 128 + 4);
; #pragma unroll
;             for (int ai = 0; ai < 2; ++ai)
; #pragma unroll
;                 for (int m = 0; m < 4; ++m) { f32x4 a, b;
; #pragma unroll
;                     for (int i = 0; i < 4; ++i) { a[i] = gelu_tanh(acc[ai][bj][m][0][i] + b0[i]); b[i] = gelu_tanh(acc[ai][bj][m][1][i] + b1[i]); }
;                     *(u32x4*)(O + (size_t)(row0 + ai * 128 + m * 16) * 256 + col0 + bj * 128) = pack8(a, b); } }
	v_mul_f32_e32 v85, v85, v90
	v_mul_f32_e32 v90, 0x3d372713, v81
	v_mul_f32_e32 v90, v81, v90
	v_fma_f32 v90, v81, v90, v81
	v_mul_f32_e32 v90, 0x3fcc422a, v90
	v_mul_f32_e32 v90, 0xbfb8aa3b, v90
	v_exp_f32_e32 v90, v90
	s_nop 0
	v_add_f32_e32 v90, 1.0, v90
	v_rcp_f32_e32 v90, v90
	s_nop 0
	v_mul_f32_e32 v81, v81, v90
	v_mul_f32_e32 v90, 0x3d372713, v86
	v_mul_f32_e32 v90, v86, v90
	v_fma_f32 v90, v86, v90, v86
	v_mul_f32_e32 v90, 0x3fcc422a, v90
	v_mul_f32_e32 v90, 0xbfb8aa3b, v90
	v_exp_f32_e32 v90, v90
	s_nop 0
	v_add_f32_e32 v90, 1.0, v90
	v_rcp_f32_e32 v90, v90
	s_nop 0
	v_mul_f32_e32 v86, v86, v90
	v_mul_f32_e32 v90, 0x3d372713, v82
	v_mul_f32_e32 v90, v82, v90
	v_fma_f32 v90, v82, v90, v82
	v_mul_f32_e32 v90, 0x3fcc422a, v90
	v_mul_f32_e32 v90, 0xbfb8aa3b, v90
	v_exp_f32_e32 v90, v90
	s_nop 0
	v_add_f32_e32 v90, 1.0, v90
	v_rcp_f32_e32 v90, v90
	s_nop 0
	v_mul_f32_e32 v90, v82, v90
	v_add_f32_e32 v82, v87, v103
	v_mul_f32_e32 v87, 0x3d372713, v82
	v_mul_f32_e32 v87, v82, v87
	v_fma_f32 v87, v82, v87, v82
	v_mul_f32_e32 v87, 0x3fcc422a, v87
	v_mul_f32_e32 v87, 0xbfb8aa3b, v87
	v_exp_f32_e32 v87, v87
	s_nop 0
	v_add_f32_e32 v87, 1.0, v87
	v_rcp_f32_e32 v87, v87
	s_nop 0
	v_mul_f32_e32 v87, v82, v87
	v_add_f32_e32 v82, v83, v99
	v_mul_f32_e32 v83, 0x3d372713, v82
	v_mul_f32_e32 v83, v82, v83
	v_fma_f32 v83, v82, v83, v82
	v_mul_f32_e32 v83, 0x3fcc422a, v83
	v_mul_f32_e32 v83, 0xbfb8aa3b, v83
	v_exp_f32_e32 v83, v83
	s_nop 0
	v_add_f32_e32 v83, 1.0, v83
	v_rcp_f32_e32 v83, v83
	s_nop 0
	v_mul_f32_e32 v91, v82, v83
	v_cvt_pk_bf16_f32 v82, v84, v85
	v_cvt_pk_bf16_f32 v83, v86, v87
	v_cvt_pk_bf16_f32 v84, v80, v81
	v_lshl_add_u64 v[80:81], v[132:133], 0, s[10:11]
	s_mov_b32 s10, 0x12000
	v_add_co_u32_e32 v86, vcc, s10, v132
	v_cvt_pk_bf16_f32 v85, v90, v91
	s_mov_b64 s[10:11], 0x14000
	s_nop 0
	v_addc_co_u32_e32 v87, vcc, 0, v133, vcc
	global_store_dwordx4 v[86:87], v[82:85], off sc1
	s_nop 1
	v_mul_f32_e32 v82, 0x3d372713, v76
	v_mul_f32_e32 v82, v76, v82
	v_fma_f32 v82, v76, v82, v76
	v_mul_f32_e32 v82, 0x3fcc422a, v82
	v_mul_f32_e32 v82, 0xbfb8aa3b, v82
	v_exp_f32_e32 v82, v82
	s_nop 0
	v_add_f32_e32 v82, 1.0, v82
	v_rcp_f32_e32 v82, v82
	s_nop 0
	v_mul_f32_e32 v76, v76, v82
	v_mul_f32_e32 v82, 0x3d372713, v72
	v_mul_f32_e32 v82, v72, v82
	v_fma_f32 v82, v72, v82, v72
	v_mul_f32_e32 v82, 0x3fcc422a, v82
	v_mul_f32_e32 v82, 0xbfb8aa3b, v82
	v_exp_f32_e32 v82, v82
	s_nop 0
	v_add_f32_e32 v82, 1.0, v82
	v_rcp_f32_e32 v82, v82
	s_nop 0
	v_mul_f32_e32 v72, v72, v82
	v_mul_f32_e32 v82, 0x3d372713, v77
	v_mul_f32_e32 v82, v77, v82
	v_fma_f32 v82, v77, v82, v77
	v_mul_f32_e32 v82, 0x3fcc422a, v82
	v_mul_f32_e32 v82, 0xbfb8aa3b, v82
	v_exp_f32_e32 v82, v82
	s_nop 0
	v_add_f32_e32 v82, 1.0, v82
	v_rcp_f32_e32 v82, v82
	s_nop 0
	v_mul_f32_e32 v77, v77, v82
	v_mul_f32_e32 v82, 0x3d372713, v73
	v_mul_f32_e32 v82, v73, v82
	v_fma_f32 v82, v73, v82, v73
	v_mul_f32_e32 v82, 0x3fcc422a, v82
	v_mul_f32_e32 v82, 0xbfb8aa3b, v82
	v_exp_f32_e32 v82, v82
	s_nop 0
	v_add_f32_e32 v82, 1.0, v82
	v_rcp_f32_e32 v82, v82
	s_nop 0
	v_mul_f32_e32 v73, v73, v82
	v_mul_f32_e32 v82, 0x3d372713, v78
	v_mul_f32_e32 v82, v78, v82
	v_fma_f32 v82, v78, v82, v78
	v_mul_f32_e32 v82, 0x3fcc422a, v82
	v_mul_f32_e32 v82, 0xbfb8aa3b, v82
	v_exp_f32_e32 v82, v82
	s_nop 0
	v_add_f32_e32 v82, 1.0, v82
	v_rcp_f32_e32 v82, v82
	s_nop 0
	v_mul_f32_e32 v78, v78, v82
	v_mul_f32_e32 v82, 0x3d372713, v74
	v_mul_f32_e32 v82, v74, v82
	v_fma_f32 v82, v74, v82, v74
	v_mul_f32_e32 v82, 0x3fcc422a, v82
	v_mul_f32_e32 v82, 0xbfb8aa3b, v82
	v_exp_f32_e32 v82, v82
	s_nop 0
	v_add_f32_e32 v82, 1.0, v82
	v_rcp_f32_e32 v82, v82
	s_nop 0
	v_mul_f32_e32 v82, v74, v82
	v_add_f32_e32 v74, v79, v103
	v_mul_f32_e32 v79, 0x3d372713, v74
	v_mul_f32_e32 v79, v74, v79
	v_fma_f32 v79, v74, v79, v74
	v_mul_f32_e32 v79, 0x3fcc422a, v79
	v_mul_f32_e32 v79, 0xbfb8aa3b, v79
	v_exp_f32_e32 v79, v79
	s_nop 0
	v_add_f32_e32 v79, 1.0, v79
	v_rcp_f32_e32 v79, v79
	s_nop 0
	v_mul_f32_e32 v79, v74, v79
	v_add_f32_e32 v74, v75, v99
	v_mul_f32_e32 v75, 0x3d372713, v74
	v_mul_f32_e32 v75, v74, v75
	v_fma_f32 v75, v74, v75, v74
	v_mul_f32_e32 v75, 0x3fcc422a, v75
	v_mul_f32_e32 v75, 0xbfb8aa3b, v75
	v_exp_f32_e32 v75, v75
	s_nop 0
	v_add_f32_e32 v75, 1.0, v75
	v_rcp_f32_e32 v75, v75
	s_nop 0
	v_mul_f32_e32 v83, v74, v75
	v_cvt_pk_bf16_f32 v74, v76, v77
	v_cvt_pk_bf16_f32 v75, v78, v79
	v_cvt_pk_bf16_f32 v76, v72, v73
	v_lshl_add_u64 v[72:73], v[132:133], 0, s[10:11]
	s_mov_b32 s10, 0x14000
	v_add_co_u32_e32 v78, vcc, s10, v132
	v_cvt_pk_bf16_f32 v77, v82, v83
	s_mov_b64 s[10:11], 0x16000
	s_nop 0
	v_addc_co_u32_e32 v79, vcc, 0, v133, vcc
	global_store_dwordx4 v[78:79], v[74:77], off sc1
	s_nop 1
	v_mul_f32_e32 v74, 0x3d372713, v68
	v_mul_f32_e32 v74, v68, v74
	v_fma_f32 v74, v68, v74, v68
	v_mul_f32_e32 v74, 0x3fcc422a, v74
	v_mul_f32_e32 v74, 0xbfb8aa3b, v74
	v_exp_f32_e32 v74, v74
	s_nop 0
	v_add_f32_e32 v74, 1.0, v74
	v_rcp_f32_e32 v74, v74
	s_nop 0
	v_mul_f32_e32 v68, v68, v74
	v_mul_f32_e32 v74, 0x3d372713, v64
	v_mul_f32_e32 v74, v64, v74
	v_fma_f32 v74, v64, v74, v64
	v_mul_f32_e32 v74, 0x3fcc422a, v74
	v_mul_f32_e32 v74, 0xbfb8aa3b, v74
	v_exp_f32_e32 v74, v74
	s_nop 0
	v_add_f32_e32 v74, 1.0, v74
	v_rcp_f32_e32 v74, v74
	s_nop 0
	v_mul_f32_e32 v74, v64, v74
	v_add_f32_e32 v64, v69, v101
	v_mul_f32_e32 v69, 0x3d372713, v64
	v_mul_f32_e32 v69, v64, v69
	v_fma_f32 v69, v64, v69, v64
	v_mul_f32_e32 v69, 0x3fcc422a, v69
	v_mul_f32_e32 v69, 0xbfb8aa3b, v69
	v_exp_f32_e32 v69, v69
	s_nop 0
	v_add_f32_e32 v69, 1.0, v69
	v_rcp_f32_e32 v69, v69
	s_nop 0
	v_mul_f32_e32 v64, v64, v69
	v_mul_f32_e32 v69, 0x3d372713, v65
; __device__ __forceinline__ float gelu_tanh(float x) { return x * sigm(1.5957691216f * (x + 0.044715f * x * x * x)); }
; __device__ __forceinline__ u32x4 pack8(f32x4 a, f32x4 b) { u32x4 o; o.x = pk2(a[0], a[1]); o.y = pk2(a[2], a[3]); o.z = pk2(b[0], b[1]); o.w = pk2(b[2], b[3]); return o; }
;     __device__ __forceinline__ void operator()(AccRef acc, const Unit& u, int wr, int wc, int fr, int fq) const {
;         const int row0 = u.pm * 256 + wr * 64 + fr, col0 = wc * 32 + 8 * fq;
; #pragma unroll
;         for (int bj = 0; bj < 2; ++bj) { const f32x4 b0 = *(const f32x4*)(bias + col0 + bj * 128), b1 = *(const f32x4*)(bias + col0 + bj * 128 + 4);
; #pragma unroll
;             for (int ai = 0; ai < 2; ++ai)
; #pragma unroll
;                 for (int m = 0; m < 4; ++m) { f32x4 a, b;
; #pragma unroll
;                     for (int i = 0; i < 4; ++i) { a[i] = gelu_tanh(acc[ai][bj][m][0][i] + b0[i]); b[i] = gelu_tanh(acc[ai][bj][m][1][i] + b1[i]); }
;                     *(u32x4*)(O + (size_t)(row0 + ai * 128 + m * 16) * 256 + col0 + bj * 128) = pack8(a, b); } }
	v_mul_f32_e32 v69, v65, v69
	v_fma_f32 v69, v65, v69, v65
	v_mul_f32_e32 v69, 0x3fcc422a, v69
	v_mul_f32_e32 v69, 0xbfb8aa3b, v69
	v_exp_f32_e32 v69, v69
	v_cvt_pk_bf16_f32 v64, v68, v64
	s_nop 0
	v_add_f32_e32 v69, 1.0, v69
	v_rcp_f32_e32 v69, v69
	s_nop 0
	v_mul_f32_e32 v69, v65, v69
	v_add_f32_e32 v65, v70, v102
	v_mul_f32_e32 v70, 0x3d372713, v65
	v_mul_f32_e32 v70, v65, v70
	v_fma_f32 v70, v65, v70, v65
	v_mul_f32_e32 v70, 0x3fcc422a, v70
	v_mul_f32_e32 v70, 0xbfb8aa3b, v70
	v_exp_f32_e32 v70, v70
	s_nop 0
	v_add_f32_e32 v70, 1.0, v70
	v_rcp_f32_e32 v70, v70
	s_nop 0
	v_mul_f32_e32 v65, v65, v70
	v_mul_f32_e32 v70, 0x3d372713, v66
	v_mul_f32_e32 v70, v66, v70
	v_fma_f32 v70, v66, v70, v66
	v_mul_f32_e32 v70, 0x3fcc422a, v70
	v_mul_f32_e32 v70, 0xbfb8aa3b, v70
	v_exp_f32_e32 v70, v70
	s_nop 0
	v_add_f32_e32 v70, 1.0, v70
	v_rcp_f32_e32 v70, v70
	s_nop 0
	v_mul_f32_e32 v70, v66, v70
	v_add_f32_e32 v66, v71, v103
	v_mul_f32_e32 v71, 0x3d372713, v66
	v_mul_f32_e32 v71, v66, v71
	v_fma_f32 v71, v66, v71, v66
	v_mul_f32_e32 v71, 0x3fcc422a, v71
	v_mul_f32_e32 v71, 0xbfb8aa3b, v71
	v_exp_f32_e32 v71, v71
	s_nop 0
	v_add_f32_e32 v71, 1.0, v71
	v_rcp_f32_e32 v71, v71
	s_nop 0
	v_mul_f32_e32 v66, v66, v71
	v_mul_f32_e32 v71, 0x3d372713, v67
	v_mul_f32_e32 v71, v67, v71
	v_fma_f32 v71, v67, v71, v67
	v_mul_f32_e32 v71, 0x3fcc422a, v71
	v_mul_f32_e32 v71, 0xbfb8aa3b, v71
	v_exp_f32_e32 v71, v71
	v_cvt_pk_bf16_f32 v65, v65, v66
	v_cvt_pk_bf16_f32 v66, v74, v69
	v_lshl_add_u64 v[74:75], v[132:133], 0, s[10:11]
	v_add_f32_e32 v71, 1.0, v71
	v_rcp_f32_e32 v71, v71
	s_mov_b32 s10, 0x16000
	v_add_co_u32_e32 v68, vcc, s10, v132
	v_mul_f32_e32 v67, v67, v71
	s_nop 0
	v_addc_co_u32_e32 v69, vcc, 0, v133, vcc
	v_cvt_pk_bf16_f32 v67, v70, v67
	global_store_dwordx4 v[68:69], v[64:67], off sc1
	global_load_dwordx4 v[64:67], v[144:145], off offset:528
	s_nop 0
	global_load_dwordx4 v[68:71], v[144:145], off offset:512
	s_andn2_b64 vcc, exec, s[6:7]
	s_waitcnt vmcnt(1)
	v_add_f32_e32 v56, v56, v64
	s_waitcnt vmcnt(0)
	v_add_f32_e32 v60, v60, v68
	v_mul_f32_e32 v76, 0x3d372713, v60
	v_mul_f32_e32 v76, v60, v76
	v_fma_f32 v76, v60, v76, v60
	v_mul_f32_e32 v76, 0x3fcc422a, v76
	v_mul_f32_e32 v76, 0xbfb8aa3b, v76
	v_exp_f32_e32 v76, v76
	v_add_f32_e32 v57, v57, v65
	v_add_f32_e32 v58, v58, v66
	v_add_f32_e32 v59, v59, v67
	v_add_f32_e32 v76, 1.0, v76
	v_rcp_f32_e32 v76, v76
	v_add_f32_e32 v52, v52, v68
	v_add_f32_e32 v48, v48, v64
	v_add_f32_e32 v49, v49, v65
	v_mul_f32_e32 v60, v60, v76
	v_mul_f32_e32 v76, 0x3d372713, v56
	v_mul_f32_e32 v76, v56, v76
	v_fma_f32 v76, v56, v76, v56
	v_mul_f32_e32 v76, 0x3fcc422a, v76
	v_mul_f32_e32 v76, 0xbfb8aa3b, v76
	v_exp_f32_e32 v76, v76
	v_add_f32_e32 v50, v50, v66
	v_add_f32_e32 v51, v51, v67
	v_add_f32_e32 v44, v44, v68
	v_add_f32_e32 v76, 1.0, v76
	v_rcp_f32_e32 v76, v76
	v_add_f32_e32 v40, v40, v64
	v_add_f32_e32 v41, v41, v65
	v_add_f32_e32 v42, v42, v66
	v_mul_f32_e32 v76, v56, v76
	v_add_f32_e32 v56, v61, v69
	v_mul_f32_e32 v61, 0x3d372713, v56
	v_mul_f32_e32 v61, v56, v61
	v_fma_f32 v61, v56, v61, v56
	v_mul_f32_e32 v61, 0x3fcc422a, v61
	v_mul_f32_e32 v61, 0xbfb8aa3b, v61
	v_exp_f32_e32 v61, v61
	v_add_f32_e32 v43, v43, v67
	v_add_f32_e32 v36, v36, v68
	v_add_f32_e32 v32, v32, v64
	v_add_f32_e32 v61, 1.0, v61
	v_rcp_f32_e32 v61, v61
	v_add_f32_e32 v33, v33, v65
	v_add_f32_e32 v34, v34, v66
	v_add_f32_e32 v35, v35, v67
	v_mul_f32_e32 v56, v56, v61
	v_mul_f32_e32 v61, 0x3d372713, v57
	v_mul_f32_e32 v61, v57, v61
	v_fma_f32 v61, v57, v61, v57
	v_mul_f32_e32 v61, 0x3fcc422a, v61
	v_mul_f32_e32 v61, 0xbfb8aa3b, v61
	v_exp_f32_e32 v61, v61
	v_cvt_pk_bf16_f32 v56, v60, v56
	v_add_f32_e32 v28, v28, v68
	v_add_f32_e32 v24, v24, v64
	v_add_f32_e32 v61, 1.0, v61
	v_rcp_f32_e32 v61, v61
	v_add_f32_e32 v25, v25, v65
	v_add_f32_e32 v26, v26, v66
	v_add_f32_e32 v27, v27, v67
	v_mul_f32_e32 v61, v57, v61
	v_add_f32_e32 v57, v62, v70
	v_mul_f32_e32 v62, 0x3d372713, v57
	v_mul_f32_e32 v62, v57, v62
	v_fma_f32 v62, v57, v62, v57
	v_mul_f32_e32 v62, 0x3fcc422a, v62
	v_mul_f32_e32 v62, 0xbfb8aa3b, v62
	v_exp_f32_e32 v62, v62
	v_add_f32_e32 v20, v20, v68
	v_add_f32_e32 v16, v16, v64
	v_add_f32_e32 v17, v17, v65
	v_add_f32_e32 v62, 1.0, v62
	v_rcp_f32_e32 v62, v62
	v_add_f32_e32 v18, v18, v66
	v_add_f32_e32 v19, v19, v67
	v_add_f32_e32 v12, v12, v68
	v_mul_f32_e32 v57, v57, v62
	v_mul_f32_e32 v62, 0x3d372713, v58
	v_mul_f32_e32 v62, v58, v62
	v_fma_f32 v62, v58, v62, v58
	v_mul_f32_e32 v62, 0x3fcc422a, v62
	v_mul_f32_e32 v62, 0xbfb8aa3b, v62
	v_exp_f32_e32 v62, v62
	v_add_f32_e32 v8, v8, v64
	v_add_f32_e32 v9, v9, v65
	v_add_f32_e32 v10, v10, v66
	v_add_f32_e32 v62, 1.0, v62
	v_rcp_f32_e32 v62, v62
	v_add_f32_e32 v11, v11, v67
	v_add_f32_e32 v4, v4, v68
	v_add_f32_e32 v0, v0, v64
	v_mul_f32_e32 v62, v58, v62
	v_add_f32_e32 v58, v63, v71
	v_mul_f32_e32 v63, 0x3d372713, v58
	v_mul_f32_e32 v63, v58, v63
	v_fma_f32 v63, v58, v63, v58
	v_mul_f32_e32 v63, 0x3fcc422a, v63
	v_mul_f32_e32 v63, 0xbfb8aa3b, v63
	v_exp_f32_e32 v63, v63
	v_add_f32_e32 v1, v1, v65
	v_add_f32_e32 v2, v2, v66
	v_add_f32_e32 v3, v3, v67
	v_add_f32_e32 v63, 1.0, v63
	v_rcp_f32_e32 v63, v63
	s_nop 0
	v_mul_f32_e32 v58, v58, v63
	v_mul_f32_e32 v63, 0x3d372713, v59
	v_mul_f32_e32 v63, v59, v63
	v_fma_f32 v63, v59, v63, v59
	v_mul_f32_e32 v63, 0x3fcc422a, v63
	v_mul_f32_e32 v63, 0xbfb8aa3b, v63
	v_exp_f32_e32 v63, v63
	v_cvt_pk_bf16_f32 v57, v57, v58
	v_cvt_pk_bf16_f32 v58, v76, v61
	s_nop 0
	v_add_f32_e32 v63, 1.0, v63
	v_rcp_f32_e32 v63, v63
	s_nop 0
	v_mul_f32_e32 v59, v59, v63
	v_cvt_pk_bf16_f32 v59, v62, v59
	global_store_dwordx4 v[132:133], v[56:59], off offset:256 sc1
; __device__ __forceinline__ float gelu_tanh(float x) { return x * sigm(1.5957691216f * (x + 0.044715f * x * x * x)); }
; __device__ __forceinline__ u32x4 pack8(f32x4 a, f32x4 b) { u32x4 o; o.x = pk2(a[0], a[1]); o.y = pk2(a[2], a[3]); o.z = pk2(b[0], b[1]); o.w = pk2(b[2], b[3]); return o; }
;     __device__ __forceinline__ void operator()(AccRef acc, const Unit& u, int wr, int wc, int fr, int fq) const {
;         const int row0 = u.pm * 256 + wr * 64 + fr, col0 = wc * 32 + 8 * fq;
; #pragma unroll
;         for (int bj = 0; bj < 2; ++bj) { const f32x4 b0 = *(const f32x4*)(bias + col0 + bj * 128), b1 = *(const f32x4*)(bias + col0 + bj * 128 + 4);
; #pragma unroll
;             for (int ai = 0; ai < 2; ++ai)
; #pragma unroll
;                 for (int m = 0; m < 4; ++m) { f32x4 a, b;
; #pragma unroll
;                     for (int i = 0; i < 4; ++i) { a[i] = gelu_tanh(acc[ai][bj][m][0][i] + b0[i]); b[i] = gelu_tanh(acc[ai][bj][m][1][i] + b1[i]); }
;                     *(u32x4*)(O + (size_t)(row0 + ai * 128 + m * 16) * 256 + col0 + bj * 128) = pack8(a, b); } }
	s_nop 1
	v_mul_f32_e32 v56, 0x3d372713, v52
	v_mul_f32_e32 v56, v52, v56
	v_fma_f32 v56, v52, v56, v52
	v_mul_f32_e32 v56, 0x3fcc422a, v56
	v_mul_f32_e32 v56, 0xbfb8aa3b, v56
	v_exp_f32_e32 v56, v56
	s_nop 0
	v_add_f32_e32 v56, 1.0, v56
	v_rcp_f32_e32 v56, v56
	s_nop 0
	v_mul_f32_e32 v52, v52, v56
	v_mul_f32_e32 v56, 0x3d372713, v48
	v_mul_f32_e32 v56, v48, v56
	v_fma_f32 v56, v48, v56, v48
	v_mul_f32_e32 v56, 0x3fcc422a, v56
	v_mul_f32_e32 v56, 0xbfb8aa3b, v56
	v_exp_f32_e32 v56, v56
	s_nop 0
	v_add_f32_e32 v56, 1.0, v56
	v_rcp_f32_e32 v56, v56
	s_nop 0
	v_mul_f32_e32 v56, v48, v56
	v_add_f32_e32 v48, v53, v69
	v_mul_f32_e32 v53, 0x3d372713, v48
	v_mul_f32_e32 v53, v48, v53
	v_fma_f32 v53, v48, v53, v48
	v_mul_f32_e32 v53, 0x3fcc422a, v53
	v_mul_f32_e32 v53, 0xbfb8aa3b, v53
	v_exp_f32_e32 v53, v53
	s_nop 0
	v_add_f32_e32 v53, 1.0, v53
	v_rcp_f32_e32 v53, v53
	s_nop 0
	v_mul_f32_e32 v48, v48, v53
	v_mul_f32_e32 v53, 0x3d372713, v49
	v_mul_f32_e32 v53, v49, v53
	v_fma_f32 v53, v49, v53, v49
	v_mul_f32_e32 v53, 0x3fcc422a, v53
	v_mul_f32_e32 v53, 0xbfb8aa3b, v53
	v_exp_f32_e32 v53, v53
	v_cvt_pk_bf16_f32 v48, v52, v48
	s_nop 0
	v_add_f32_e32 v53, 1.0, v53
	v_rcp_f32_e32 v53, v53
	s_nop 0
	v_mul_f32_e32 v53, v49, v53
	v_add_f32_e32 v49, v54, v70
	v_mul_f32_e32 v54, 0x3d372713, v49
	v_mul_f32_e32 v54, v49, v54
	v_fma_f32 v54, v49, v54, v49
	v_mul_f32_e32 v54, 0x3fcc422a, v54
	v_mul_f32_e32 v54, 0xbfb8aa3b, v54
	v_exp_f32_e32 v54, v54
	s_nop 0
	v_add_f32_e32 v54, 1.0, v54
	v_rcp_f32_e32 v54, v54
	s_nop 0
	v_mul_f32_e32 v49, v49, v54
	v_mul_f32_e32 v54, 0x3d372713, v50
	v_mul_f32_e32 v54, v50, v54
	v_fma_f32 v54, v50, v54, v50
	v_mul_f32_e32 v54, 0x3fcc422a, v54
	v_mul_f32_e32 v54, 0xbfb8aa3b, v54
	v_exp_f32_e32 v54, v54
	s_nop 0
	v_add_f32_e32 v54, 1.0, v54
	v_rcp_f32_e32 v54, v54
	s_nop 0
	v_mul_f32_e32 v54, v50, v54
	v_add_f32_e32 v50, v55, v71
	v_mul_f32_e32 v55, 0x3d372713, v50
	v_mul_f32_e32 v55, v50, v55
	v_fma_f32 v55, v50, v55, v50
	v_mul_f32_e32 v55, 0x3fcc422a, v55
	v_mul_f32_e32 v55, 0xbfb8aa3b, v55
	v_exp_f32_e32 v55, v55
	s_nop 0
	v_add_f32_e32 v55, 1.0, v55
	v_rcp_f32_e32 v55, v55
	s_nop 0
	v_mul_f32_e32 v50, v50, v55
	v_mul_f32_e32 v55, 0x3d372713, v51
	v_mul_f32_e32 v55, v51, v55
	v_fma_f32 v55, v51, v55, v51
	v_mul_f32_e32 v55, 0x3fcc422a, v55
	v_mul_f32_e32 v55, 0xbfb8aa3b, v55
	v_exp_f32_e32 v55, v55
	v_cvt_pk_bf16_f32 v49, v49, v50
	v_cvt_pk_bf16_f32 v50, v56, v53
	s_nop 0
	v_add_f32_e32 v55, 1.0, v55
	v_rcp_f32_e32 v55, v55
	s_nop 0
	v_mul_f32_e32 v51, v51, v55
	v_cvt_pk_bf16_f32 v51, v54, v51
	global_store_dwordx4 v[120:121], v[48:51], off offset:256 sc1
	s_nop 1
	v_mul_f32_e32 v48, 0x3d372713, v44
	v_mul_f32_e32 v48, v44, v48
	v_fma_f32 v48, v44, v48, v44
	v_mul_f32_e32 v48, 0x3fcc422a, v48
	v_mul_f32_e32 v48, 0xbfb8aa3b, v48
	v_exp_f32_e32 v48, v48
	s_nop 0
	v_add_f32_e32 v48, 1.0, v48
	v_rcp_f32_e32 v48, v48
	s_nop 0
	v_mul_f32_e32 v44, v44, v48
	v_mul_f32_e32 v48, 0x3d372713, v40
	v_mul_f32_e32 v48, v40, v48
	v_fma_f32 v48, v40, v48, v40
	v_mul_f32_e32 v48, 0x3fcc422a, v48
	v_mul_f32_e32 v48, 0xbfb8aa3b, v48
	v_exp_f32_e32 v48, v48
	s_nop 0
	v_add_f32_e32 v48, 1.0, v48
	v_rcp_f32_e32 v48, v48
	s_nop 0
	v_mul_f32_e32 v48, v40, v48
	v_add_f32_e32 v40, v45, v69
	v_mul_f32_e32 v45, 0x3d372713, v40
	v_mul_f32_e32 v45, v40, v45
	v_fma_f32 v45, v40, v45, v40
	v_mul_f32_e32 v45, 0x3fcc422a, v45
	v_mul_f32_e32 v45, 0xbfb8aa3b, v45
	v_exp_f32_e32 v45, v45
	s_nop 0
	v_add_f32_e32 v45, 1.0, v45
	v_rcp_f32_e32 v45, v45
	s_nop 0
	v_mul_f32_e32 v40, v40, v45
	v_mul_f32_e32 v45, 0x3d372713, v41
	v_mul_f32_e32 v45, v41, v45
	v_fma_f32 v45, v41, v45, v41
	v_mul_f32_e32 v45, 0x3fcc422a, v45
	v_mul_f32_e32 v45, 0xbfb8aa3b, v45
	v_exp_f32_e32 v45, v45
	v_cvt_pk_bf16_f32 v40, v44, v40
	s_nop 0
	v_add_f32_e32 v45, 1.0, v45
	v_rcp_f32_e32 v45, v45
	s_nop 0
	v_mul_f32_e32 v45, v41, v45
	v_add_f32_e32 v41, v46, v70
	v_mul_f32_e32 v46, 0x3d372713, v41
	v_mul_f32_e32 v46, v41, v46
	v_fma_f32 v46, v41, v46, v41
	v_mul_f32_e32 v46, 0x3fcc422a, v46
	v_mul_f32_e32 v46, 0xbfb8aa3b, v46
	v_exp_f32_e32 v46, v46
	s_nop 0
	v_add_f32_e32 v46, 1.0, v46
	v_rcp_f32_e32 v46, v46
	s_nop 0
	v_mul_f32_e32 v41, v41, v46
	v_mul_f32_e32 v46, 0x3d372713, v42
	v_mul_f32_e32 v46, v42, v46
	v_fma_f32 v46, v42, v46, v42
	v_mul_f32_e32 v46, 0x3fcc422a, v46
	v_mul_f32_e32 v46, 0xbfb8aa3b, v46
	v_exp_f32_e32 v46, v46
	s_nop 0
	v_add_f32_e32 v46, 1.0, v46
	v_rcp_f32_e32 v46, v46
	s_nop 0
	v_mul_f32_e32 v46, v42, v46
	v_add_f32_e32 v42, v47, v71
	v_mul_f32_e32 v47, 0x3d372713, v42
	v_mul_f32_e32 v47, v42, v47
	v_fma_f32 v47, v42, v47, v42
	v_mul_f32_e32 v47, 0x3fcc422a, v47
	v_mul_f32_e32 v47, 0xbfb8aa3b, v47
	v_exp_f32_e32 v47, v47
	s_nop 0
	v_add_f32_e32 v47, 1.0, v47
	v_rcp_f32_e32 v47, v47
	s_nop 0
	v_mul_f32_e32 v42, v42, v47
	v_mul_f32_e32 v47, 0x3d372713, v43
	v_mul_f32_e32 v47, v43, v47
	v_fma_f32 v47, v43, v47, v43
	v_mul_f32_e32 v47, 0x3fcc422a, v47
	v_mul_f32_e32 v47, 0xbfb8aa3b, v47
	v_exp_f32_e32 v47, v47
	v_cvt_pk_bf16_f32 v41, v41, v42
	v_cvt_pk_bf16_f32 v42, v48, v45
	s_nop 0
	v_add_f32_e32 v47, 1.0, v47
	v_rcp_f32_e32 v47, v47
	s_nop 0
	v_mul_f32_e32 v43, v43, v47
	v_cvt_pk_bf16_f32 v43, v46, v43
	global_store_dwordx4 v[112:113], v[40:43], off offset:256 sc1
	s_nop 1
	v_mul_f32_e32 v40, 0x3d372713, v36
	v_mul_f32_e32 v40, v36, v40
	v_fma_f32 v40, v36, v40, v36
	v_mul_f32_e32 v40, 0x3fcc422a, v40
	v_mul_f32_e32 v40, 0xbfb8aa3b, v40
	v_exp_f32_e32 v40, v40
	s_nop 0
	v_add_f32_e32 v40, 1.0, v40
	v_rcp_f32_e32 v40, v40
	s_nop 0
	v_mul_f32_e32 v36, v36, v40
	v_mul_f32_e32 v40, 0x3d372713, v32
	v_mul_f32_e32 v40, v32, v40
	v_fma_f32 v40, v32, v40, v32
; __device__ __forceinline__ float gelu_tanh(float x) { return x * sigm(1.5957691216f * (x + 0.044715f * x * x * x)); }
; __device__ __forceinline__ u32x4 pack8(f32x4 a, f32x4 b) { u32x4 o; o.x = pk2(a[0], a[1]); o.y = pk2(a[2], a[3]); o.z = pk2(b[0], b[1]); o.w = pk2(b[2], b[3]); return o; }
;     __device__ __forceinline__ void operator()(AccRef acc, const Unit& u, int wr, int wc, int fr, int fq) const {
;         const int row0 = u.pm * 256 + wr * 64 + fr, col0 = wc * 32 + 8 * fq;
; #pragma unroll
;         for (int bj = 0; bj < 2; ++bj) { const f32x4 b0 = *(const f32x4*)(bias + col0 + bj * 128), b1 = *(const f32x4*)(bias + col0 + bj * 128 + 4);
; #pragma unroll
;             for (int ai = 0; ai < 2; ++ai)
; #pragma unroll
;                 for (int m = 0; m < 4; ++m) { f32x4 a, b;
; #pragma unroll
;                     for (int i = 0; i < 4; ++i) { a[i] = gelu_tanh(acc[ai][bj][m][0][i] + b0[i]); b[i] = gelu_tanh(acc[ai][bj][m][1][i] + b1[i]); }
;                     *(u32x4*)(O + (size_t)(row0 + ai * 128 + m * 16) * 256 + col0 + bj * 128) = pack8(a, b); } }
	v_mul_f32_e32 v40, 0x3fcc422a, v40
	v_mul_f32_e32 v40, 0xbfb8aa3b, v40
	v_exp_f32_e32 v40, v40
	s_nop 0
	v_add_f32_e32 v40, 1.0, v40
	v_rcp_f32_e32 v40, v40
	s_nop 0
	v_mul_f32_e32 v40, v32, v40
	v_add_f32_e32 v32, v37, v69
	v_mul_f32_e32 v37, 0x3d372713, v32
	v_mul_f32_e32 v37, v32, v37
	v_fma_f32 v37, v32, v37, v32
	v_mul_f32_e32 v37, 0x3fcc422a, v37
	v_mul_f32_e32 v37, 0xbfb8aa3b, v37
	v_exp_f32_e32 v37, v37
	s_nop 0
	v_add_f32_e32 v37, 1.0, v37
	v_rcp_f32_e32 v37, v37
	s_nop 0
	v_mul_f32_e32 v32, v32, v37
	v_mul_f32_e32 v37, 0x3d372713, v33
	v_mul_f32_e32 v37, v33, v37
	v_fma_f32 v37, v33, v37, v33
	v_mul_f32_e32 v37, 0x3fcc422a, v37
	v_mul_f32_e32 v37, 0xbfb8aa3b, v37
	v_exp_f32_e32 v37, v37
	v_cvt_pk_bf16_f32 v32, v36, v32
	s_nop 0
	v_add_f32_e32 v37, 1.0, v37
	v_rcp_f32_e32 v37, v37
	s_nop 0
	v_mul_f32_e32 v37, v33, v37
	v_add_f32_e32 v33, v38, v70
	v_mul_f32_e32 v38, 0x3d372713, v33
	v_mul_f32_e32 v38, v33, v38
	v_fma_f32 v38, v33, v38, v33
	v_mul_f32_e32 v38, 0x3fcc422a, v38
	v_mul_f32_e32 v38, 0xbfb8aa3b, v38
	v_exp_f32_e32 v38, v38
	s_nop 0
	v_add_f32_e32 v38, 1.0, v38
	v_rcp_f32_e32 v38, v38
	s_nop 0
	v_mul_f32_e32 v33, v33, v38
	v_mul_f32_e32 v38, 0x3d372713, v34
	v_mul_f32_e32 v38, v34, v38
	v_fma_f32 v38, v34, v38, v34
	v_mul_f32_e32 v38, 0x3fcc422a, v38
	v_mul_f32_e32 v38, 0xbfb8aa3b, v38
	v_exp_f32_e32 v38, v38
	s_nop 0
	v_add_f32_e32 v38, 1.0, v38
	v_rcp_f32_e32 v38, v38
	s_nop 0
	v_mul_f32_e32 v38, v34, v38
	v_add_f32_e32 v34, v39, v71
	v_mul_f32_e32 v39, 0x3d372713, v34
	v_mul_f32_e32 v39, v34, v39
	v_fma_f32 v39, v34, v39, v34
	v_mul_f32_e32 v39, 0x3fcc422a, v39
	v_mul_f32_e32 v39, 0xbfb8aa3b, v39
	v_exp_f32_e32 v39, v39
	s_nop 0
	v_add_f32_e32 v39, 1.0, v39
	v_rcp_f32_e32 v39, v39
	s_nop 0
	v_mul_f32_e32 v34, v34, v39
	v_mul_f32_e32 v39, 0x3d372713, v35
	v_mul_f32_e32 v39, v35, v39
	v_fma_f32 v39, v35, v39, v35
	v_mul_f32_e32 v39, 0x3fcc422a, v39
	v_mul_f32_e32 v39, 0xbfb8aa3b, v39
	v_exp_f32_e32 v39, v39
	v_cvt_pk_bf16_f32 v33, v33, v34
	v_cvt_pk_bf16_f32 v34, v40, v37
	s_nop 0
	v_add_f32_e32 v39, 1.0, v39
	v_rcp_f32_e32 v39, v39
	s_nop 0
	v_mul_f32_e32 v35, v35, v39
	v_cvt_pk_bf16_f32 v35, v38, v35
	global_store_dwordx4 v[104:105], v[32:35], off offset:256 sc1
	s_nop 1
	v_mul_f32_e32 v32, 0x3d372713, v28
	v_mul_f32_e32 v32, v28, v32
	v_fma_f32 v32, v28, v32, v28
	v_mul_f32_e32 v32, 0x3fcc422a, v32
	v_mul_f32_e32 v32, 0xbfb8aa3b, v32
	v_exp_f32_e32 v32, v32
	s_nop 0
	v_add_f32_e32 v32, 1.0, v32
	v_rcp_f32_e32 v32, v32
	s_nop 0
	v_mul_f32_e32 v28, v28, v32
	v_mul_f32_e32 v32, 0x3d372713, v24
	v_mul_f32_e32 v32, v24, v32
	v_fma_f32 v32, v24, v32, v24
	v_mul_f32_e32 v32, 0x3fcc422a, v32
	v_mul_f32_e32 v32, 0xbfb8aa3b, v32
	v_exp_f32_e32 v32, v32
	s_nop 0
	v_add_f32_e32 v32, 1.0, v32
	v_rcp_f32_e32 v32, v32
	s_nop 0
	v_mul_f32_e32 v32, v24, v32
	v_add_f32_e32 v24, v29, v69
	v_mul_f32_e32 v29, 0x3d372713, v24
	v_mul_f32_e32 v29, v24, v29
	v_fma_f32 v29, v24, v29, v24
	v_mul_f32_e32 v29, 0x3fcc422a, v29
	v_mul_f32_e32 v29, 0xbfb8aa3b, v29
	v_exp_f32_e32 v29, v29
	s_nop 0
	v_add_f32_e32 v29, 1.0, v29
	v_rcp_f32_e32 v29, v29
	s_nop 0
	v_mul_f32_e32 v24, v24, v29
	v_mul_f32_e32 v29, 0x3d372713, v25
	v_mul_f32_e32 v29, v25, v29
	v_fma_f32 v29, v25, v29, v25
	v_mul_f32_e32 v29, 0x3fcc422a, v29
	v_mul_f32_e32 v29, 0xbfb8aa3b, v29
	v_exp_f32_e32 v29, v29
	v_cvt_pk_bf16_f32 v24, v28, v24
	s_nop 0
	v_add_f32_e32 v29, 1.0, v29
	v_rcp_f32_e32 v29, v29
	s_nop 0
	v_mul_f32_e32 v29, v25, v29
	v_add_f32_e32 v25, v30, v70
	v_mul_f32_e32 v30, 0x3d372713, v25
	v_mul_f32_e32 v30, v25, v30
	v_fma_f32 v30, v25, v30, v25
	v_mul_f32_e32 v30, 0x3fcc422a, v30
	v_mul_f32_e32 v30, 0xbfb8aa3b, v30
	v_exp_f32_e32 v30, v30
	s_nop 0
	v_add_f32_e32 v30, 1.0, v30
	v_rcp_f32_e32 v30, v30
	s_nop 0
	v_mul_f32_e32 v25, v25, v30
	v_mul_f32_e32 v30, 0x3d372713, v26
	v_mul_f32_e32 v30, v26, v30
	v_fma_f32 v30, v26, v30, v26
	v_mul_f32_e32 v30, 0x3fcc422a, v30
	v_mul_f32_e32 v30, 0xbfb8aa3b, v30
	v_exp_f32_e32 v30, v30
	s_nop 0
	v_add_f32_e32 v30, 1.0, v30
	v_rcp_f32_e32 v30, v30
	s_nop 0
	v_mul_f32_e32 v30, v26, v30
	v_add_f32_e32 v26, v31, v71
	v_mul_f32_e32 v31, 0x3d372713, v26
	v_mul_f32_e32 v31, v26, v31
	v_fma_f32 v31, v26, v31, v26
	v_mul_f32_e32 v31, 0x3fcc422a, v31
	v_mul_f32_e32 v31, 0xbfb8aa3b, v31
	v_exp_f32_e32 v31, v31
	s_nop 0
	v_add_f32_e32 v31, 1.0, v31
	v_rcp_f32_e32 v31, v31
	s_nop 0
	v_mul_f32_e32 v26, v26, v31
	v_mul_f32_e32 v31, 0x3d372713, v27
	v_mul_f32_e32 v31, v27, v31
	v_fma_f32 v31, v27, v31, v27
	v_mul_f32_e32 v31, 0x3fcc422a, v31
	v_mul_f32_e32 v31, 0xbfb8aa3b, v31
	v_exp_f32_e32 v31, v31
	v_cvt_pk_bf16_f32 v25, v25, v26
	v_cvt_pk_bf16_f32 v26, v32, v29
	s_nop 0
	v_add_f32_e32 v31, 1.0, v31
	v_rcp_f32_e32 v31, v31
	s_nop 0
	v_mul_f32_e32 v27, v27, v31
	v_cvt_pk_bf16_f32 v27, v30, v27
	global_store_dwordx4 v[88:89], v[24:27], off offset:256 sc1
	s_nop 1
	v_mul_f32_e32 v24, 0x3d372713, v20
	v_mul_f32_e32 v24, v20, v24
	v_fma_f32 v24, v20, v24, v20
	v_mul_f32_e32 v24, 0x3fcc422a, v24
	v_mul_f32_e32 v24, 0xbfb8aa3b, v24
	v_exp_f32_e32 v24, v24
	s_nop 0
	v_add_f32_e32 v24, 1.0, v24
	v_rcp_f32_e32 v24, v24
	s_nop 0
	v_mul_f32_e32 v20, v20, v24
	v_mul_f32_e32 v24, 0x3d372713, v16
	v_mul_f32_e32 v24, v16, v24
	v_fma_f32 v24, v16, v24, v16
	v_mul_f32_e32 v24, 0x3fcc422a, v24
	v_mul_f32_e32 v24, 0xbfb8aa3b, v24
	v_exp_f32_e32 v24, v24
	s_nop 0
	v_add_f32_e32 v24, 1.0, v24
	v_rcp_f32_e32 v24, v24
	s_nop 0
	v_mul_f32_e32 v24, v16, v24
	v_add_f32_e32 v16, v21, v69
	v_mul_f32_e32 v21, 0x3d372713, v16
	v_mul_f32_e32 v21, v16, v21
	v_fma_f32 v21, v16, v21, v16
	v_mul_f32_e32 v21, 0x3fcc422a, v21
	v_mul_f32_e32 v21, 0xbfb8aa3b, v21
; __device__ __forceinline__ float gelu_tanh(float x) { return x * sigm(1.5957691216f * (x + 0.044715f * x * x * x)); }
; __device__ __forceinline__ u32x4 pack8(f32x4 a, f32x4 b) { u32x4 o; o.x = pk2(a[0], a[1]); o.y = pk2(a[2], a[3]); o.z = pk2(b[0], b[1]); o.w = pk2(b[2], b[3]); return o; }
;     __device__ __forceinline__ void operator()(AccRef acc, const Unit& u, int wr, int wc, int fr, int fq) const {
;     ...
;         for (int bj = 0; bj < 2; ++bj) { const f32x4 b0 = *(const f32x4*)(bias + col0 + bj * 128), b1 = *(const f32x4*)(bias + col0 + bj * 128 + 4);
; #pragma unroll
;             for (int ai = 0; ai < 2; ++ai)
; #pragma unroll
;                 for (int m = 0; m < 4; ++m) { f32x4 a, b;
; #pragma unroll
;                     for (int i = 0; i < 4; ++i) { a[i] = gelu_tanh(acc[ai][bj][m][0][i] + b0[i]); b[i] = gelu_tanh(acc[ai][bj][m][1][i] + b1[i]); }
;                     *(u32x4*)(O + (size_t)(row0 + ai * 128 + m * 16) * 256 + col0 + bj * 128) = pack8(a, b); } }
	v_exp_f32_e32 v21, v21
	s_nop 0
	v_add_f32_e32 v21, 1.0, v21
	v_rcp_f32_e32 v21, v21
	s_nop 0
	v_mul_f32_e32 v16, v16, v21
	v_mul_f32_e32 v21, 0x3d372713, v17
	v_mul_f32_e32 v21, v17, v21
	v_fma_f32 v21, v17, v21, v17
	v_mul_f32_e32 v21, 0x3fcc422a, v21
	v_mul_f32_e32 v21, 0xbfb8aa3b, v21
	v_exp_f32_e32 v21, v21
	v_cvt_pk_bf16_f32 v16, v20, v16
	s_nop 0
	v_add_f32_e32 v21, 1.0, v21
	v_rcp_f32_e32 v21, v21
	s_nop 0
	v_mul_f32_e32 v21, v17, v21
	v_add_f32_e32 v17, v22, v70
	v_mul_f32_e32 v22, 0x3d372713, v17
	v_mul_f32_e32 v22, v17, v22
	v_fma_f32 v22, v17, v22, v17
	v_mul_f32_e32 v22, 0x3fcc422a, v22
	v_mul_f32_e32 v22, 0xbfb8aa3b, v22
	v_exp_f32_e32 v22, v22
	s_nop 0
	v_add_f32_e32 v22, 1.0, v22
	v_rcp_f32_e32 v22, v22
	s_nop 0
	v_mul_f32_e32 v17, v17, v22
	v_mul_f32_e32 v22, 0x3d372713, v18
	v_mul_f32_e32 v22, v18, v22
	v_fma_f32 v22, v18, v22, v18
	v_mul_f32_e32 v22, 0x3fcc422a, v22
	v_mul_f32_e32 v22, 0xbfb8aa3b, v22
	v_exp_f32_e32 v22, v22
	s_nop 0
	v_add_f32_e32 v22, 1.0, v22
	v_rcp_f32_e32 v22, v22
	s_nop 0
	v_mul_f32_e32 v22, v18, v22
	v_add_f32_e32 v18, v23, v71
	v_mul_f32_e32 v23, 0x3d372713, v18
	v_mul_f32_e32 v23, v18, v23
	v_fma_f32 v23, v18, v23, v18
	v_mul_f32_e32 v23, 0x3fcc422a, v23
	v_mul_f32_e32 v23, 0xbfb8aa3b, v23
	v_exp_f32_e32 v23, v23
	s_nop 0
	v_add_f32_e32 v23, 1.0, v23
	v_rcp_f32_e32 v23, v23
	s_nop 0
	v_mul_f32_e32 v18, v18, v23
	v_mul_f32_e32 v23, 0x3d372713, v19
	v_mul_f32_e32 v23, v19, v23
	v_fma_f32 v23, v19, v23, v19
	v_mul_f32_e32 v23, 0x3fcc422a, v23
	v_mul_f32_e32 v23, 0xbfb8aa3b, v23
	v_exp_f32_e32 v23, v23
	v_cvt_pk_bf16_f32 v17, v17, v18
	v_cvt_pk_bf16_f32 v18, v24, v21
	s_nop 0
	v_add_f32_e32 v23, 1.0, v23
	v_rcp_f32_e32 v23, v23
	s_nop 0
	v_mul_f32_e32 v19, v19, v23
	v_cvt_pk_bf16_f32 v19, v22, v19
	global_store_dwordx4 v[80:81], v[16:19], off offset:256 sc1
	s_nop 1
	v_mul_f32_e32 v16, 0x3d372713, v12
	v_mul_f32_e32 v16, v12, v16
	v_fma_f32 v16, v12, v16, v12
	v_mul_f32_e32 v16, 0x3fcc422a, v16
	v_mul_f32_e32 v16, 0xbfb8aa3b, v16
	v_exp_f32_e32 v16, v16
	s_nop 0
	v_add_f32_e32 v16, 1.0, v16
	v_rcp_f32_e32 v16, v16
	s_nop 0
	v_mul_f32_e32 v12, v12, v16
	v_mul_f32_e32 v16, 0x3d372713, v8
	v_mul_f32_e32 v16, v8, v16
	v_fma_f32 v16, v8, v16, v8
	v_mul_f32_e32 v16, 0x3fcc422a, v16
	v_mul_f32_e32 v16, 0xbfb8aa3b, v16
	v_exp_f32_e32 v16, v16
	s_nop 0
	v_add_f32_e32 v16, 1.0, v16
	v_rcp_f32_e32 v16, v16
	s_nop 0
	v_mul_f32_e32 v16, v8, v16
	v_add_f32_e32 v8, v13, v69
	v_mul_f32_e32 v13, 0x3d372713, v8
	v_mul_f32_e32 v13, v8, v13
	v_fma_f32 v13, v8, v13, v8
	v_mul_f32_e32 v13, 0x3fcc422a, v13
	v_mul_f32_e32 v13, 0xbfb8aa3b, v13
	v_exp_f32_e32 v13, v13
	s_nop 0
	v_add_f32_e32 v13, 1.0, v13
	v_rcp_f32_e32 v13, v13
	s_nop 0
	v_mul_f32_e32 v8, v8, v13
	v_mul_f32_e32 v13, 0x3d372713, v9
	v_mul_f32_e32 v13, v9, v13
	v_fma_f32 v13, v9, v13, v9
	v_mul_f32_e32 v13, 0x3fcc422a, v13
	v_mul_f32_e32 v13, 0xbfb8aa3b, v13
	v_exp_f32_e32 v13, v13
	v_cvt_pk_bf16_f32 v8, v12, v8
	s_nop 0
	v_add_f32_e32 v13, 1.0, v13
	v_rcp_f32_e32 v13, v13
	s_nop 0
	v_mul_f32_e32 v13, v9, v13
	v_add_f32_e32 v9, v14, v70
	v_mul_f32_e32 v14, 0x3d372713, v9
	v_mul_f32_e32 v14, v9, v14
	v_fma_f32 v14, v9, v14, v9
	v_mul_f32_e32 v14, 0x3fcc422a, v14
	v_mul_f32_e32 v14, 0xbfb8aa3b, v14
	v_exp_f32_e32 v14, v14
	s_nop 0
	v_add_f32_e32 v14, 1.0, v14
	v_rcp_f32_e32 v14, v14
	s_nop 0
	v_mul_f32_e32 v9, v9, v14
	v_mul_f32_e32 v14, 0x3d372713, v10
	v_mul_f32_e32 v14, v10, v14
	v_fma_f32 v14, v10, v14, v10
	v_mul_f32_e32 v14, 0x3fcc422a, v14
	v_mul_f32_e32 v14, 0xbfb8aa3b, v14
	v_exp_f32_e32 v14, v14
	s_nop 0
	v_add_f32_e32 v14, 1.0, v14
	v_rcp_f32_e32 v14, v14
	s_nop 0
	v_mul_f32_e32 v14, v10, v14
	v_add_f32_e32 v10, v15, v71
	v_mul_f32_e32 v15, 0x3d372713, v10
	v_mul_f32_e32 v15, v10, v15
	v_fma_f32 v15, v10, v15, v10
	v_mul_f32_e32 v15, 0x3fcc422a, v15
	v_mul_f32_e32 v15, 0xbfb8aa3b, v15
	v_exp_f32_e32 v15, v15
	s_nop 0
	v_add_f32_e32 v15, 1.0, v15
	v_rcp_f32_e32 v15, v15
	s_nop 0
	v_mul_f32_e32 v10, v10, v15
	v_mul_f32_e32 v15, 0x3d372713, v11
	v_mul_f32_e32 v15, v11, v15
	v_fma_f32 v15, v11, v15, v11
	v_mul_f32_e32 v15, 0x3fcc422a, v15
	v_mul_f32_e32 v15, 0xbfb8aa3b, v15
	v_exp_f32_e32 v15, v15
	v_cvt_pk_bf16_f32 v9, v9, v10
	v_cvt_pk_bf16_f32 v10, v16, v13
	s_nop 0
	v_add_f32_e32 v15, 1.0, v15
	v_rcp_f32_e32 v15, v15
	s_nop 0
	v_mul_f32_e32 v11, v11, v15
	v_cvt_pk_bf16_f32 v11, v14, v11
	global_store_dwordx4 v[72:73], v[8:11], off offset:256 sc1
	s_nop 1
	v_mul_f32_e32 v8, 0x3d372713, v4
	v_mul_f32_e32 v8, v4, v8
	v_fma_f32 v8, v4, v8, v4
	v_mul_f32_e32 v8, 0x3fcc422a, v8
	v_mul_f32_e32 v8, 0xbfb8aa3b, v8
	v_exp_f32_e32 v8, v8
	s_nop 0
	v_add_f32_e32 v8, 1.0, v8
	v_rcp_f32_e32 v8, v8
	s_nop 0
	v_mul_f32_e32 v4, v4, v8
	v_mul_f32_e32 v8, 0x3d372713, v0
	v_mul_f32_e32 v8, v0, v8
	v_fma_f32 v8, v0, v8, v0
	v_mul_f32_e32 v8, 0x3fcc422a, v8
	v_mul_f32_e32 v8, 0xbfb8aa3b, v8
	v_exp_f32_e32 v8, v8
	s_nop 0
	v_add_f32_e32 v8, 1.0, v8
	v_rcp_f32_e32 v8, v8
	s_nop 0
	v_mul_f32_e32 v8, v0, v8
	v_add_f32_e32 v0, v5, v69
	v_mul_f32_e32 v5, 0x3d372713, v0
	v_mul_f32_e32 v5, v0, v5
	v_fma_f32 v5, v0, v5, v0
	v_mul_f32_e32 v5, 0x3fcc422a, v5
	v_mul_f32_e32 v5, 0xbfb8aa3b, v5
	v_exp_f32_e32 v5, v5
	s_nop 0
	v_add_f32_e32 v5, 1.0, v5
	v_rcp_f32_e32 v5, v5
	s_nop 0
	v_mul_f32_e32 v0, v0, v5
	v_mul_f32_e32 v5, 0x3d372713, v1
	v_mul_f32_e32 v5, v1, v5
	v_fma_f32 v5, v1, v5, v1
	v_mul_f32_e32 v5, 0x3fcc422a, v5
	v_mul_f32_e32 v5, 0xbfb8aa3b, v5
	v_exp_f32_e32 v5, v5
	v_cvt_pk_bf16_f32 v0, v4, v0
	s_nop 0
	v_add_f32_e32 v5, 1.0, v5
	v_rcp_f32_e32 v5, v5
	s_nop 0
	v_mul_f32_e32 v5, v1, v5
	v_add_f32_e32 v1, v6, v70
	v_mul_f32_e32 v6, 0x3d372713, v1
	v_mul_f32_e32 v6, v1, v6
	v_fma_f32 v6, v1, v6, v1
	v_mul_f32_e32 v6, 0x3fcc422a, v6
	v_mul_f32_e32 v6, 0xbfb8aa3b, v6
	v_exp_f32_e32 v6, v6
	s_nop 0
	v_add_f32_e32 v6, 1.0, v6
	v_rcp_f32_e32 v6, v6
	s_nop 0
	v_mul_f32_e32 v1, v1, v6
	v_mul_f32_e32 v6, 0x3d372713, v2
	v_mul_f32_e32 v6, v2, v6
	v_fma_f32 v6, v2, v6, v2
	v_mul_f32_e32 v6, 0x3fcc422a, v6
	v_mul_f32_e32 v6, 0xbfb8aa3b, v6
	v_exp_f32_e32 v6, v6
	s_nop 0
	v_add_f32_e32 v6, 1.0, v6
	v_rcp_f32_e32 v6, v6
	s_nop 0
	v_mul_f32_e32 v6, v2, v6
	v_add_f32_e32 v2, v7, v71
	v_mul_f32_e32 v7, 0x3d372713, v2
	v_mul_f32_e32 v7, v2, v7
	v_fma_f32 v7, v2, v7, v2
	v_mul_f32_e32 v7, 0x3fcc422a, v7
	v_mul_f32_e32 v7, 0xbfb8aa3b, v7
	v_exp_f32_e32 v7, v7
	s_nop 0
	v_add_f32_e32 v7, 1.0, v7
	v_rcp_f32_e32 v7, v7
	s_nop 0
	v_mul_f32_e32 v2, v2, v7
	v_mul_f32_e32 v7, 0x3d372713, v3
	v_mul_f32_e32 v7, v3, v7
	v_fma_f32 v7, v3, v7, v3
	v_mul_f32_e32 v7, 0x3fcc422a, v7
	v_mul_f32_e32 v7, 0xbfb8aa3b, v7
	v_exp_f32_e32 v7, v7
	v_cvt_pk_bf16_f32 v1, v1, v2
	v_cvt_pk_bf16_f32 v2, v8, v5
	s_nop 0
	v_add_f32_e32 v7, 1.0, v7
	v_rcp_f32_e32 v7, v7
	s_nop 0
	v_mul_f32_e32 v3, v3, v7
	v_cvt_pk_bf16_f32 v3, v6, v3
	global_store_dwordx4 v[74:75], v[0:3], off offset:256 sc1
	s_cbranch_vccnz .LBB0_527
	s_andn2_b64 vcc, exec, s[0:1]
	s_cbranch_vccnz .LBB0_526
	s_barrier
	s_branch .LBB0_526

; __device__ __forceinline__ float gelu_tanh(float x) { return x * sigm(1.5957691216f * (x + 0.044715f * x * x * x)); }
; __device__ __forceinline__ u32x4 pack8(f32x4 a, f32x4 b) { u32x4 o; o.x = pk2(a[0], a[1]); o.y = pk2(a[2], a[3]); o.z = pk2(b[0], b[1]); o.w = pk2(b[2], b[3]); return o; }
;     __device__ __forceinline__ void operator()(AccRef acc, const Unit& u, int wr, int wc, int fr, int fq) const {
;     ...
;         for (int bj = 0; bj < 2; ++bj) { const f32x4 b0 = *(const f32x4*)(bias + col0 + bj * 128), b1 = *(const f32x4*)(bias + col0 + bj * 128 + 4);
; #pragma unroll
;             for (int ai = 0; ai < 2; ++ai)
; #pragma unroll
;                 for (int m = 0; m < 4; ++m) { f32x4 a, b;
; #pragma unroll
;                     for (int i = 0; i < 4; ++i) { a[i] = gelu_tanh(acc[ai][bj][m][0][i] + b0[i]); b[i] = gelu_tanh(acc[ai][bj][m][1][i] + b1[i]); }
;                     *(u32x4*)(O + (size_t)(row0 + ai * 128 + m * 16) * 256 + col0 + bj * 128) = pack8(a, b); } }
.LBB0_562:
	global_load_dwordx4 v[96:99], v[144:145], off offset:16
	global_load_dwordx4 v[100:103], v[144:145], off
	v_lshl_add_u32 v152, s54, 8, v155
	s_mov_b64 s[10:11], 0x10000
	s_mov_b64 s[14:15], -1
	s_waitcnt vmcnt(0)
	v_add_f32_e32 v128, v128, v96
	v_add_f32_e32 v132, v132, v100
	v_mul_f32_e32 v153, 0x3d372713, v132
	v_mul_f32_e32 v153, v132, v153
	v_fma_f32 v153, v132, v153, v132
	v_mul_f32_e32 v153, 0x3fcc422a, v153
	v_mul_f32_e32 v153, 0xbfb8aa3b, v153
	v_exp_f32_e32 v153, v153
	v_add_f32_e32 v129, v129, v97
	v_add_f32_e32 v130, v130, v98
	v_add_f32_e32 v131, v131, v99
	v_add_f32_e32 v153, 1.0, v153
	v_rcp_f32_e32 v153, v153
	v_add_f32_e32 v124, v124, v100
	v_add_f32_e32 v120, v120, v96
	v_add_f32_e32 v125, v125, v101
	v_mul_f32_e32 v132, v132, v153
	v_mul_f32_e32 v153, 0x3d372713, v128
	v_mul_f32_e32 v153, v128, v153
	v_fma_f32 v153, v128, v153, v128
	v_mul_f32_e32 v153, 0x3fcc422a, v153
	v_mul_f32_e32 v153, 0xbfb8aa3b, v153
	v_exp_f32_e32 v153, v153
	v_add_f32_e32 v121, v121, v97
	v_add_f32_e32 v126, v126, v102
	v_add_f32_e32 v122, v122, v98
	v_add_f32_e32 v153, 1.0, v153
	v_rcp_f32_e32 v153, v153
	v_add_f32_e32 v116, v116, v100
	v_add_f32_e32 v112, v112, v96
	v_add_f32_e32 v117, v117, v101
	v_mul_f32_e32 v153, v128, v153
	v_add_f32_e32 v128, v133, v101
	v_mul_f32_e32 v133, 0x3d372713, v128
	v_mul_f32_e32 v133, v128, v133
	v_fma_f32 v133, v128, v133, v128
	v_mul_f32_e32 v133, 0x3fcc422a, v133
	v_mul_f32_e32 v133, 0xbfb8aa3b, v133
	v_exp_f32_e32 v133, v133
	v_add_f32_e32 v113, v113, v97
	v_add_f32_e32 v118, v118, v102
	v_add_f32_e32 v114, v114, v98
	v_add_f32_e32 v133, 1.0, v133
	v_rcp_f32_e32 v133, v133
	v_add_f32_e32 v108, v108, v100
	v_add_f32_e32 v104, v104, v96
	v_add_f32_e32 v109, v109, v101
	v_mul_f32_e32 v128, v128, v133
	v_mul_f32_e32 v133, 0x3d372713, v129
	v_mul_f32_e32 v133, v129, v133
	v_fma_f32 v133, v129, v133, v129
	v_mul_f32_e32 v133, 0x3fcc422a, v133
	v_mul_f32_e32 v133, 0xbfb8aa3b, v133
	v_exp_f32_e32 v133, v133
	v_cvt_pk_bf16_f32 v128, v132, v128
	v_add_f32_e32 v105, v105, v97
	v_add_f32_e32 v110, v110, v102
	v_add_f32_e32 v133, 1.0, v133
	v_rcp_f32_e32 v133, v133
	v_add_f32_e32 v106, v106, v98
	v_add_f32_e32 v92, v92, v100
	v_add_f32_e32 v88, v88, v96
	v_mul_f32_e32 v133, v129, v133
	v_add_f32_e32 v129, v134, v102
	v_mul_f32_e32 v134, 0x3d372713, v129
	v_mul_f32_e32 v134, v129, v134
	v_fma_f32 v134, v129, v134, v129
	v_mul_f32_e32 v134, 0x3fcc422a, v134
	v_mul_f32_e32 v134, 0xbfb8aa3b, v134
	v_exp_f32_e32 v134, v134
	v_add_f32_e32 v93, v93, v101
	v_add_f32_e32 v89, v89, v97
	v_add_f32_e32 v94, v94, v102
	v_add_f32_e32 v134, 1.0, v134
	v_rcp_f32_e32 v134, v134
	v_add_f32_e32 v90, v90, v98
	v_add_f32_e32 v84, v84, v100
	v_add_f32_e32 v80, v80, v96
	v_mul_f32_e32 v129, v129, v134
	v_mul_f32_e32 v134, 0x3d372713, v130
	v_mul_f32_e32 v134, v130, v134
	v_fma_f32 v134, v130, v134, v130
	v_mul_f32_e32 v134, 0x3fcc422a, v134
	v_mul_f32_e32 v134, 0xbfb8aa3b, v134
	v_exp_f32_e32 v134, v134
	v_add_f32_e32 v85, v85, v101
	v_add_f32_e32 v81, v81, v97
	v_add_f32_e32 v86, v86, v102
	v_add_f32_e32 v134, 1.0, v134
	v_rcp_f32_e32 v134, v134
	v_add_f32_e32 v82, v82, v98
	v_add_f32_e32 v76, v76, v100
	v_add_f32_e32 v72, v72, v96
	v_mul_f32_e32 v134, v130, v134
	v_add_f32_e32 v130, v135, v103
	v_mul_f32_e32 v135, 0x3d372713, v130
	v_mul_f32_e32 v135, v130, v135
	v_fma_f32 v135, v130, v135, v130
	v_mul_f32_e32 v135, 0x3fcc422a, v135
	v_mul_f32_e32 v135, 0xbfb8aa3b, v135
	v_exp_f32_e32 v135, v135
	v_add_f32_e32 v77, v77, v101
	v_add_f32_e32 v73, v73, v97
	v_add_f32_e32 v78, v78, v102
	v_add_f32_e32 v135, 1.0, v135
	v_rcp_f32_e32 v135, v135
	v_add_f32_e32 v74, v74, v98
	v_add_f32_e32 v68, v68, v100
	v_add_f32_e32 v64, v64, v96
	v_mul_f32_e32 v130, v130, v135
	v_mul_f32_e32 v135, 0x3d372713, v131
	v_mul_f32_e32 v135, v131, v135
	v_fma_f32 v135, v131, v135, v131
	v_mul_f32_e32 v135, 0x3fcc422a, v135
	v_mul_f32_e32 v135, 0xbfb8aa3b, v135
	v_exp_f32_e32 v135, v135
	v_cvt_pk_bf16_f32 v129, v129, v130
	v_cvt_pk_bf16_f32 v130, v153, v133
	v_ashrrev_i32_e32 v153, 31, v152
	v_add_f32_e32 v135, 1.0, v135
	v_rcp_f32_e32 v135, v135
	v_lshlrev_b64 v[132:133], 9, v[152:153]
	v_lshl_add_u64 v[132:133], v[146:147], 0, v[132:133]
	v_add_f32_e32 v65, v65, v97
	v_mul_f32_e32 v131, v131, v135
	v_cvt_pk_bf16_f32 v131, v134, v131
	global_store_dwordx4 v[132:133], v[128:131], off sc1
	v_add_f32_e32 v66, v66, v98
	v_add_f32_e32 v67, v67, v99
	v_mul_f32_e32 v128, 0x3d372713, v124
	v_mul_f32_e32 v128, v124, v128
	v_fma_f32 v128, v124, v128, v124
	v_mul_f32_e32 v128, 0x3fcc422a, v128
	v_mul_f32_e32 v128, 0xbfb8aa3b, v128
	v_exp_f32_e32 v128, v128
	s_nop 0
	v_add_f32_e32 v128, 1.0, v128
	v_rcp_f32_e32 v128, v128
	s_nop 0
	v_mul_f32_e32 v124, v124, v128
	v_mul_f32_e32 v128, 0x3d372713, v120
	v_mul_f32_e32 v128, v120, v128
	v_fma_f32 v128, v120, v128, v120
	v_mul_f32_e32 v128, 0x3fcc422a, v128
	v_mul_f32_e32 v128, 0xbfb8aa3b, v128
	v_exp_f32_e32 v128, v128
	s_nop 0
	v_add_f32_e32 v128, 1.0, v128
	v_rcp_f32_e32 v128, v128
	s_nop 0
	v_mul_f32_e32 v120, v120, v128
	v_mul_f32_e32 v128, 0x3d372713, v125
	v_mul_f32_e32 v128, v125, v128
	v_fma_f32 v128, v125, v128, v125
	v_mul_f32_e32 v128, 0x3fcc422a, v128
	v_mul_f32_e32 v128, 0xbfb8aa3b, v128
	v_exp_f32_e32 v128, v128
	s_nop 0
	v_add_f32_e32 v128, 1.0, v128
	v_rcp_f32_e32 v128, v128
	s_nop 0
	v_mul_f32_e32 v125, v125, v128
	v_mul_f32_e32 v128, 0x3d372713, v121
	v_mul_f32_e32 v128, v121, v128
	v_fma_f32 v128, v121, v128, v121
	v_mul_f32_e32 v128, 0x3fcc422a, v128
	v_mul_f32_e32 v128, 0xbfb8aa3b, v128
	v_exp_f32_e32 v128, v128
	s_nop 0
	v_add_f32_e32 v128, 1.0, v128
	v_rcp_f32_e32 v128, v128
	s_nop 0
; __device__ __forceinline__ float gelu_tanh(float x) { return x * sigm(1.5957691216f * (x + 0.044715f * x * x * x)); }
; __device__ __forceinline__ u32x4 pack8(f32x4 a, f32x4 b) { u32x4 o; o.x = pk2(a[0], a[1]); o.y = pk2(a[2], a[3]); o.z = pk2(b[0], b[1]); o.w = pk2(b[2], b[3]); return o; }
;     __device__ __forceinline__ void operator()(AccRef acc, const Unit& u, int wr, int wc, int fr, int fq) const {
;     ...
;         for (int bj = 0; bj < 2; ++bj) { const f32x4 b0 = *(const f32x4*)(bias + col0 + bj * 128), b1 = *(const f32x4*)(bias + col0 + bj * 128 + 4);
; #pragma unroll
;             for (int ai = 0; ai < 2; ++ai)
; #pragma unroll
;                 for (int m = 0; m < 4; ++m) { f32x4 a, b;
; #pragma unroll
;                     for (int i = 0; i < 4; ++i) { a[i] = gelu_tanh(acc[ai][bj][m][0][i] + b0[i]); b[i] = gelu_tanh(acc[ai][bj][m][1][i] + b1[i]); }
;                     *(u32x4*)(O + (size_t)(row0 + ai * 128 + m * 16) * 256 + col0 + bj * 128) = pack8(a, b); } }
	v_mul_f32_e32 v121, v121, v128
	v_mul_f32_e32 v128, 0x3d372713, v126
	v_mul_f32_e32 v128, v126, v128
	v_fma_f32 v128, v126, v128, v126
	v_mul_f32_e32 v128, 0x3fcc422a, v128
	v_mul_f32_e32 v128, 0xbfb8aa3b, v128
	v_exp_f32_e32 v128, v128
	s_nop 0
	v_add_f32_e32 v128, 1.0, v128
	v_rcp_f32_e32 v128, v128
	s_nop 0
	v_mul_f32_e32 v126, v126, v128
	v_mul_f32_e32 v128, 0x3d372713, v122
	v_mul_f32_e32 v128, v122, v128
	v_fma_f32 v128, v122, v128, v122
	v_mul_f32_e32 v128, 0x3fcc422a, v128
	v_mul_f32_e32 v128, 0xbfb8aa3b, v128
	v_exp_f32_e32 v128, v128
	s_nop 0
	v_add_f32_e32 v128, 1.0, v128
	v_rcp_f32_e32 v128, v128
	s_nop 0
	v_mul_f32_e32 v128, v122, v128
	v_add_f32_e32 v122, v127, v103
	v_mul_f32_e32 v127, 0x3d372713, v122
	v_mul_f32_e32 v127, v122, v127
	v_fma_f32 v127, v122, v127, v122
	v_mul_f32_e32 v127, 0x3fcc422a, v127
	v_mul_f32_e32 v127, 0xbfb8aa3b, v127
	v_exp_f32_e32 v127, v127
	s_nop 0
	v_add_f32_e32 v127, 1.0, v127
	v_rcp_f32_e32 v127, v127
	s_nop 0
	v_mul_f32_e32 v127, v122, v127
	v_add_f32_e32 v122, v123, v99
	v_mul_f32_e32 v123, 0x3d372713, v122
	v_mul_f32_e32 v123, v122, v123
	v_fma_f32 v123, v122, v123, v122
	v_mul_f32_e32 v123, 0x3fcc422a, v123
	v_mul_f32_e32 v123, 0xbfb8aa3b, v123
	v_exp_f32_e32 v123, v123
	s_nop 0
	v_add_f32_e32 v123, 1.0, v123
	v_rcp_f32_e32 v123, v123
	s_nop 0
	v_mul_f32_e32 v129, v122, v123
	v_cvt_pk_bf16_f32 v122, v124, v125
	v_cvt_pk_bf16_f32 v123, v126, v127
	v_cvt_pk_bf16_f32 v124, v120, v121
	v_or_b32_e32 v120, 16, v152
	v_ashrrev_i32_e32 v121, 31, v120
	v_lshlrev_b64 v[120:121], 9, v[120:121]
	v_lshl_add_u64 v[120:121], v[146:147], 0, v[120:121]
	v_cvt_pk_bf16_f32 v125, v128, v129
	global_store_dwordx4 v[120:121], v[122:125], off sc1
	s_nop 1
	v_mul_f32_e32 v122, 0x3d372713, v116
	v_mul_f32_e32 v122, v116, v122
	v_fma_f32 v122, v116, v122, v116
	v_mul_f32_e32 v122, 0x3fcc422a, v122
	v_mul_f32_e32 v122, 0xbfb8aa3b, v122
	v_exp_f32_e32 v122, v122
	s_nop 0
	v_add_f32_e32 v122, 1.0, v122
	v_rcp_f32_e32 v122, v122
	s_nop 0
	v_mul_f32_e32 v116, v116, v122
	v_mul_f32_e32 v122, 0x3d372713, v112
	v_mul_f32_e32 v122, v112, v122
	v_fma_f32 v122, v112, v122, v112
	v_mul_f32_e32 v122, 0x3fcc422a, v122
	v_mul_f32_e32 v122, 0xbfb8aa3b, v122
	v_exp_f32_e32 v122, v122
	s_nop 0
	v_add_f32_e32 v122, 1.0, v122
	v_rcp_f32_e32 v122, v122
	s_nop 0
	v_mul_f32_e32 v112, v112, v122
	v_mul_f32_e32 v122, 0x3d372713, v117
	v_mul_f32_e32 v122, v117, v122
	v_fma_f32 v122, v117, v122, v117
	v_mul_f32_e32 v122, 0x3fcc422a, v122
	v_mul_f32_e32 v122, 0xbfb8aa3b, v122
	v_exp_f32_e32 v122, v122
	s_nop 0
	v_add_f32_e32 v122, 1.0, v122
	v_rcp_f32_e32 v122, v122
	s_nop 0
	v_mul_f32_e32 v117, v117, v122
	v_mul_f32_e32 v122, 0x3d372713, v113
	v_mul_f32_e32 v122, v113, v122
	v_fma_f32 v122, v113, v122, v113
	v_mul_f32_e32 v122, 0x3fcc422a, v122
	v_mul_f32_e32 v122, 0xbfb8aa3b, v122
	v_exp_f32_e32 v122, v122
	s_nop 0
	v_add_f32_e32 v122, 1.0, v122
	v_rcp_f32_e32 v122, v122
	s_nop 0
	v_mul_f32_e32 v113, v113, v122
	v_mul_f32_e32 v122, 0x3d372713, v118
	v_mul_f32_e32 v122, v118, v122
	v_fma_f32 v122, v118, v122, v118
	v_mul_f32_e32 v122, 0x3fcc422a, v122
	v_mul_f32_e32 v122, 0xbfb8aa3b, v122
	v_exp_f32_e32 v122, v122
	s_nop 0
	v_add_f32_e32 v122, 1.0, v122
	v_rcp_f32_e32 v122, v122
	s_nop 0
	v_mul_f32_e32 v118, v118, v122
	v_mul_f32_e32 v122, 0x3d372713, v114
	v_mul_f32_e32 v122, v114, v122
	v_fma_f32 v122, v114, v122, v114
	v_mul_f32_e32 v122, 0x3fcc422a, v122
	v_mul_f32_e32 v122, 0xbfb8aa3b, v122
	v_exp_f32_e32 v122, v122
	s_nop 0
	v_add_f32_e32 v122, 1.0, v122
	v_rcp_f32_e32 v122, v122
	s_nop 0
	v_mul_f32_e32 v122, v114, v122
	v_add_f32_e32 v114, v119, v103
	v_mul_f32_e32 v119, 0x3d372713, v114
	v_mul_f32_e32 v119, v114, v119
	v_fma_f32 v119, v114, v119, v114
	v_mul_f32_e32 v119, 0x3fcc422a, v119
	v_mul_f32_e32 v119, 0xbfb8aa3b, v119
	v_exp_f32_e32 v119, v119
	s_nop 0
	v_add_f32_e32 v119, 1.0, v119
	v_rcp_f32_e32 v119, v119
	s_nop 0
	v_mul_f32_e32 v119, v114, v119
	v_add_f32_e32 v114, v115, v99
	v_mul_f32_e32 v115, 0x3d372713, v114
	v_mul_f32_e32 v115, v114, v115
	v_fma_f32 v115, v114, v115, v114
	v_mul_f32_e32 v115, 0x3fcc422a, v115
	v_mul_f32_e32 v115, 0xbfb8aa3b, v115
	v_exp_f32_e32 v115, v115
	s_nop 0
	v_add_f32_e32 v115, 1.0, v115
	v_rcp_f32_e32 v115, v115
	s_nop 0
	v_mul_f32_e32 v123, v114, v115
	v_cvt_pk_bf16_f32 v114, v116, v117
	v_cvt_pk_bf16_f32 v115, v118, v119
	v_cvt_pk_bf16_f32 v116, v112, v113
	v_or_b32_e32 v112, 32, v152
	v_ashrrev_i32_e32 v113, 31, v112
	v_lshlrev_b64 v[112:113], 9, v[112:113]
	v_lshl_add_u64 v[112:113], v[146:147], 0, v[112:113]
	v_cvt_pk_bf16_f32 v117, v122, v123
	global_store_dwordx4 v[112:113], v[114:117], off sc1
	s_nop 1
	v_mul_f32_e32 v114, 0x3d372713, v108
	v_mul_f32_e32 v114, v108, v114
	v_fma_f32 v114, v108, v114, v108
	v_mul_f32_e32 v114, 0x3fcc422a, v114
	v_mul_f32_e32 v114, 0xbfb8aa3b, v114
	v_exp_f32_e32 v114, v114
	s_nop 0
	v_add_f32_e32 v114, 1.0, v114
	v_rcp_f32_e32 v114, v114
	s_nop 0
	v_mul_f32_e32 v108, v108, v114
	v_mul_f32_e32 v114, 0x3d372713, v104
	v_mul_f32_e32 v114, v104, v114
	v_fma_f32 v114, v104, v114, v104
	v_mul_f32_e32 v114, 0x3fcc422a, v114
	v_mul_f32_e32 v114, 0xbfb8aa3b, v114
	v_exp_f32_e32 v114, v114
	s_nop 0
	v_add_f32_e32 v114, 1.0, v114
	v_rcp_f32_e32 v114, v114
	s_nop 0
	v_mul_f32_e32 v104, v104, v114
	v_mul_f32_e32 v114, 0x3d372713, v109
	v_mul_f32_e32 v114, v109, v114
	v_fma_f32 v114, v109, v114, v109
	v_mul_f32_e32 v114, 0x3fcc422a, v114
	v_mul_f32_e32 v114, 0xbfb8aa3b, v114
	v_exp_f32_e32 v114, v114
	s_nop 0
	v_add_f32_e32 v114, 1.0, v114
	v_rcp_f32_e32 v114, v114
	s_nop 0
	v_mul_f32_e32 v109, v109, v114
	v_mul_f32_e32 v114, 0x3d372713, v105
	v_mul_f32_e32 v114, v105, v114
; __device__ __forceinline__ float gelu_tanh(float x) { return x * sigm(1.5957691216f * (x + 0.044715f * x * x * x)); }
; __device__ __forceinline__ u32x4 pack8(f32x4 a, f32x4 b) { u32x4 o; o.x = pk2(a[0], a[1]); o.y = pk2(a[2], a[3]); o.z = pk2(b[0], b[1]); o.w = pk2(b[2], b[3]); return o; }
;     __device__ __forceinline__ void operator()(AccRef acc, const Unit& u, int wr, int wc, int fr, int fq) const {
;     ...
;         for (int bj = 0; bj < 2; ++bj) { const f32x4 b0 = *(const f32x4*)(bias + col0 + bj * 128), b1 = *(const f32x4*)(bias + col0 + bj * 128 + 4);
; #pragma unroll
;             for (int ai = 0; ai < 2; ++ai)
; #pragma unroll
;                 for (int m = 0; m < 4; ++m) { f32x4 a, b;
; #pragma unroll
;                     for (int i = 0; i < 4; ++i) { a[i] = gelu_tanh(acc[ai][bj][m][0][i] + b0[i]); b[i] = gelu_tanh(acc[ai][bj][m][1][i] + b1[i]); }
;                     *(u32x4*)(O + (size_t)(row0 + ai * 128 + m * 16) * 256 + col0 + bj * 128) = pack8(a, b); } }
	v_fma_f32 v114, v105, v114, v105
	v_mul_f32_e32 v114, 0x3fcc422a, v114
	v_mul_f32_e32 v114, 0xbfb8aa3b, v114
	v_exp_f32_e32 v114, v114
	s_nop 0
	v_add_f32_e32 v114, 1.0, v114
	v_rcp_f32_e32 v114, v114
	s_nop 0
	v_mul_f32_e32 v105, v105, v114
	v_mul_f32_e32 v114, 0x3d372713, v110
	v_mul_f32_e32 v114, v110, v114
	v_fma_f32 v114, v110, v114, v110
	v_mul_f32_e32 v114, 0x3fcc422a, v114
	v_mul_f32_e32 v114, 0xbfb8aa3b, v114
	v_exp_f32_e32 v114, v114
	s_nop 0
	v_add_f32_e32 v114, 1.0, v114
	v_rcp_f32_e32 v114, v114
	s_nop 0
	v_mul_f32_e32 v110, v110, v114
	v_mul_f32_e32 v114, 0x3d372713, v106
	v_mul_f32_e32 v114, v106, v114
	v_fma_f32 v114, v106, v114, v106
	v_mul_f32_e32 v114, 0x3fcc422a, v114
	v_mul_f32_e32 v114, 0xbfb8aa3b, v114
	v_exp_f32_e32 v114, v114
	s_nop 0
	v_add_f32_e32 v114, 1.0, v114
	v_rcp_f32_e32 v114, v114
	s_nop 0
	v_mul_f32_e32 v114, v106, v114
	v_add_f32_e32 v106, v111, v103
	v_mul_f32_e32 v111, 0x3d372713, v106
	v_mul_f32_e32 v111, v106, v111
	v_fma_f32 v111, v106, v111, v106
	v_mul_f32_e32 v111, 0x3fcc422a, v111
	v_mul_f32_e32 v111, 0xbfb8aa3b, v111
	v_exp_f32_e32 v111, v111
	s_nop 0
	v_add_f32_e32 v111, 1.0, v111
	v_rcp_f32_e32 v111, v111
	s_nop 0
	v_mul_f32_e32 v111, v106, v111
	v_add_f32_e32 v106, v107, v99
	v_mul_f32_e32 v107, 0x3d372713, v106
	v_mul_f32_e32 v107, v106, v107
	v_fma_f32 v107, v106, v107, v106
	v_mul_f32_e32 v107, 0x3fcc422a, v107
	v_mul_f32_e32 v107, 0xbfb8aa3b, v107
	v_exp_f32_e32 v107, v107
	s_nop 0
	v_add_f32_e32 v107, 1.0, v107
	v_rcp_f32_e32 v107, v107
	s_nop 0
	v_mul_f32_e32 v115, v106, v107
	v_cvt_pk_bf16_f32 v106, v108, v109
	v_cvt_pk_bf16_f32 v107, v110, v111
	v_cvt_pk_bf16_f32 v108, v104, v105
	v_or_b32_e32 v104, 48, v152
	v_ashrrev_i32_e32 v105, 31, v104
	v_lshlrev_b64 v[104:105], 9, v[104:105]
	v_lshl_add_u64 v[104:105], v[146:147], 0, v[104:105]
	v_cvt_pk_bf16_f32 v109, v114, v115
	global_store_dwordx4 v[104:105], v[106:109], off sc1
	s_nop 1
	v_mul_f32_e32 v106, 0x3d372713, v92
	v_mul_f32_e32 v106, v92, v106
	v_fma_f32 v106, v92, v106, v92
	v_mul_f32_e32 v106, 0x3fcc422a, v106
	v_mul_f32_e32 v106, 0xbfb8aa3b, v106
	v_exp_f32_e32 v106, v106
	s_nop 0
	v_add_f32_e32 v106, 1.0, v106
	v_rcp_f32_e32 v106, v106
	s_nop 0
	v_mul_f32_e32 v92, v92, v106
	v_mul_f32_e32 v106, 0x3d372713, v88
	v_mul_f32_e32 v106, v88, v106
	v_fma_f32 v106, v88, v106, v88
	v_mul_f32_e32 v106, 0x3fcc422a, v106
	v_mul_f32_e32 v106, 0xbfb8aa3b, v106
	v_exp_f32_e32 v106, v106
	s_nop 0
	v_add_f32_e32 v106, 1.0, v106
	v_rcp_f32_e32 v106, v106
	s_nop 0
	v_mul_f32_e32 v88, v88, v106
	v_mul_f32_e32 v106, 0x3d372713, v93
	v_mul_f32_e32 v106, v93, v106
	v_fma_f32 v106, v93, v106, v93
	v_mul_f32_e32 v106, 0x3fcc422a, v106
	v_mul_f32_e32 v106, 0xbfb8aa3b, v106
	v_exp_f32_e32 v106, v106
	s_nop 0
	v_add_f32_e32 v106, 1.0, v106
	v_rcp_f32_e32 v106, v106
	s_nop 0
	v_mul_f32_e32 v93, v93, v106
	v_mul_f32_e32 v106, 0x3d372713, v89
	v_mul_f32_e32 v106, v89, v106
	v_fma_f32 v106, v89, v106, v89
	v_mul_f32_e32 v106, 0x3fcc422a, v106
	v_mul_f32_e32 v106, 0xbfb8aa3b, v106
	v_exp_f32_e32 v106, v106
	s_nop 0
	v_add_f32_e32 v106, 1.0, v106
	v_rcp_f32_e32 v106, v106
	s_nop 0
	v_mul_f32_e32 v89, v89, v106
	v_mul_f32_e32 v106, 0x3d372713, v94
	v_mul_f32_e32 v106, v94, v106
	v_fma_f32 v106, v94, v106, v94
	v_mul_f32_e32 v106, 0x3fcc422a, v106
	v_mul_f32_e32 v106, 0xbfb8aa3b, v106
	v_exp_f32_e32 v106, v106
	s_nop 0
	v_add_f32_e32 v106, 1.0, v106
	v_rcp_f32_e32 v106, v106
	s_nop 0
	v_mul_f32_e32 v94, v94, v106
	v_mul_f32_e32 v106, 0x3d372713, v90
	v_mul_f32_e32 v106, v90, v106
	v_fma_f32 v106, v90, v106, v90
	v_mul_f32_e32 v106, 0x3fcc422a, v106
	v_mul_f32_e32 v106, 0xbfb8aa3b, v106
	v_exp_f32_e32 v106, v106
	s_nop 0
	v_add_f32_e32 v106, 1.0, v106
	v_rcp_f32_e32 v106, v106
	s_nop 0
	v_mul_f32_e32 v106, v90, v106
	v_add_f32_e32 v90, v95, v103
	v_mul_f32_e32 v95, 0x3d372713, v90
	v_mul_f32_e32 v95, v90, v95
	v_fma_f32 v95, v90, v95, v90
	v_mul_f32_e32 v95, 0x3fcc422a, v95
	v_mul_f32_e32 v95, 0xbfb8aa3b, v95
	v_exp_f32_e32 v95, v95
	s_nop 0
	v_add_f32_e32 v95, 1.0, v95
	v_rcp_f32_e32 v95, v95
	s_nop 0
	v_mul_f32_e32 v95, v90, v95
	v_add_f32_e32 v90, v91, v99
	v_mul_f32_e32 v91, 0x3d372713, v90
	v_mul_f32_e32 v91, v90, v91
	v_fma_f32 v91, v90, v91, v90
	v_mul_f32_e32 v91, 0x3fcc422a, v91
	v_mul_f32_e32 v91, 0xbfb8aa3b, v91
	v_exp_f32_e32 v91, v91
	s_nop 0
	v_add_f32_e32 v91, 1.0, v91
	v_rcp_f32_e32 v91, v91
	s_nop 0
	v_mul_f32_e32 v107, v90, v91
	v_cvt_pk_bf16_f32 v90, v92, v93
	v_cvt_pk_bf16_f32 v91, v94, v95
	v_cvt_pk_bf16_f32 v92, v88, v89
	v_lshl_add_u64 v[88:89], v[132:133], 0, s[10:11]
	s_mov_b32 s10, 0x10000
	v_add_co_u32_e32 v94, vcc, s10, v132
	v_cvt_pk_bf16_f32 v93, v106, v107
	s_mov_b64 s[10:11], 0x12000
	s_nop 0
	v_addc_co_u32_e32 v95, vcc, 0, v133, vcc
	global_store_dwordx4 v[94:95], v[90:93], off sc1
	s_nop 1
	v_mul_f32_e32 v90, 0x3d372713, v84
	v_mul_f32_e32 v90, v84, v90
	v_fma_f32 v90, v84, v90, v84
	v_mul_f32_e32 v90, 0x3fcc422a, v90
	v_mul_f32_e32 v90, 0xbfb8aa3b, v90
	v_exp_f32_e32 v90, v90
	s_nop 0
	v_add_f32_e32 v90, 1.0, v90
	v_rcp_f32_e32 v90, v90
	s_nop 0
	v_mul_f32_e32 v84, v84, v90
	v_mul_f32_e32 v90, 0x3d372713, v80
	v_mul_f32_e32 v90, v80, v90
	v_fma_f32 v90, v80, v90, v80
	v_mul_f32_e32 v90, 0x3fcc422a, v90
	v_mul_f32_e32 v90, 0xbfb8aa3b, v90
	v_exp_f32_e32 v90, v90
	s_nop 0
	v_add_f32_e32 v90, 1.0, v90
	v_rcp_f32_e32 v90, v90
	s_nop 0
	v_mul_f32_e32 v80, v80, v90
	v_mul_f32_e32 v90, 0x3d372713, v85
	v_mul_f32_e32 v90, v85, v90
	v_fma_f32 v90, v85, v90, v85
	v_mul_f32_e32 v90, 0x3fcc422a, v90
	v_mul_f32_e32 v90, 0xbfb8aa3b, v90
	v_exp_f32_e32 v90, v90
	s_nop 0
	v_add_f32_e32 v90, 1.0, v90
	v_rcp_f32_e32 v90, v90
	s_nop 0
; __device__ __forceinline__ float gelu_tanh(float x) { return x * sigm(1.5957691216f * (x + 0.044715f * x * x * x)); }
; __device__ __forceinline__ u32x4 pack8(f32x4 a, f32x4 b) { u32x4 o; o.x = pk2(a[0], a[1]); o.y = pk2(a[2], a[3]); o.z = pk2(b[0], b[1]); o.w = pk2(b[2], b[3]); return o; }
;     __device__ __forceinline__ void operator()(AccRef acc, const Unit& u, int wr, int wc, int fr, int fq) const {
;     ...
;         for (int bj = 0; bj < 2; ++bj) { const f32x4 b0 = *(const f32x4*)(bias + col0 + bj * 128), b1 = *(const f32x4*)(bias + col0 + bj * 128 + 4);
; #pragma unroll
;             for (int ai = 0; ai < 2; ++ai)
; #pragma unroll
;                 for (int m = 0; m < 4; ++m) { f32x4 a, b;
; #pragma unroll
;                     for (int i = 0; i < 4; ++i) { a[i] = gelu_tanh(acc[ai][bj][m][0][i] + b0[i]); b[i] = gelu_tanh(acc[ai][bj][m][1][i] + b1[i]); }
;                     *(u32x4*)(O + (size_t)(row0 + ai * 128 + m * 16) * 256 + col0 + bj * 128) = pack8(a, b); } }
	v_mul_f32_e32 v85, v85, v90
	v_mul_f32_e32 v90, 0x3d372713, v81
	v_mul_f32_e32 v90, v81, v90
	v_fma_f32 v90, v81, v90, v81
	v_mul_f32_e32 v90, 0x3fcc422a, v90
	v_mul_f32_e32 v90, 0xbfb8aa3b, v90
	v_exp_f32_e32 v90, v90
	s_nop 0
	v_add_f32_e32 v90, 1.0, v90
	v_rcp_f32_e32 v90, v90
	s_nop 0
	v_mul_f32_e32 v81, v81, v90
	v_mul_f32_e32 v90, 0x3d372713, v86
	v_mul_f32_e32 v90, v86, v90
	v_fma_f32 v90, v86, v90, v86
	v_mul_f32_e32 v90, 0x3fcc422a, v90
	v_mul_f32_e32 v90, 0xbfb8aa3b, v90
	v_exp_f32_e32 v90, v90
	s_nop 0
	v_add_f32_e32 v90, 1.0, v90
	v_rcp_f32_e32 v90, v90
	s_nop 0
	v_mul_f32_e32 v86, v86, v90
	v_mul_f32_e32 v90, 0x3d372713, v82
	v_mul_f32_e32 v90, v82, v90
	v_fma_f32 v90, v82, v90, v82
	v_mul_f32_e32 v90, 0x3fcc422a, v90
	v_mul_f32_e32 v90, 0xbfb8aa3b, v90
	v_exp_f32_e32 v90, v90
	s_nop 0
	v_add_f32_e32 v90, 1.0, v90
	v_rcp_f32_e32 v90, v90
	s_nop 0
	v_mul_f32_e32 v90, v82, v90
	v_add_f32_e32 v82, v87, v103
	v_mul_f32_e32 v87, 0x3d372713, v82
	v_mul_f32_e32 v87, v82, v87
	v_fma_f32 v87, v82, v87, v82
	v_mul_f32_e32 v87, 0x3fcc422a, v87
	v_mul_f32_e32 v87, 0xbfb8aa3b, v87
	v_exp_f32_e32 v87, v87
	s_nop 0
	v_add_f32_e32 v87, 1.0, v87
	v_rcp_f32_e32 v87, v87
	s_nop 0
	v_mul_f32_e32 v87, v82, v87
	v_add_f32_e32 v82, v83, v99
	v_mul_f32_e32 v83, 0x3d372713, v82
	v_mul_f32_e32 v83, v82, v83
	v_fma_f32 v83, v82, v83, v82
	v_mul_f32_e32 v83, 0x3fcc422a, v83
	v_mul_f32_e32 v83, 0xbfb8aa3b, v83
	v_exp_f32_e32 v83, v83
	s_nop 0
	v_add_f32_e32 v83, 1.0, v83
	v_rcp_f32_e32 v83, v83
	s_nop 0
	v_mul_f32_e32 v91, v82, v83
	v_cvt_pk_bf16_f32 v82, v84, v85
	v_cvt_pk_bf16_f32 v83, v86, v87
	v_cvt_pk_bf16_f32 v84, v80, v81
	v_lshl_add_u64 v[80:81], v[132:133], 0, s[10:11]
	s_mov_b32 s10, 0x12000
	v_add_co_u32_e32 v86, vcc, s10, v132
	v_cvt_pk_bf16_f32 v85, v90, v91
	s_mov_b64 s[10:11], 0x14000
	s_nop 0
	v_addc_co_u32_e32 v87, vcc, 0, v133, vcc
	global_store_dwordx4 v[86:87], v[82:85], off sc1
	s_nop 1
	v_mul_f32_e32 v82, 0x3d372713, v76
	v_mul_f32_e32 v82, v76, v82
	v_fma_f32 v82, v76, v82, v76
	v_mul_f32_e32 v82, 0x3fcc422a, v82
	v_mul_f32_e32 v82, 0xbfb8aa3b, v82
	v_exp_f32_e32 v82, v82
	s_nop 0
	v_add_f32_e32 v82, 1.0, v82
	v_rcp_f32_e32 v82, v82
	s_nop 0
	v_mul_f32_e32 v76, v76, v82
	v_mul_f32_e32 v82, 0x3d372713, v72
	v_mul_f32_e32 v82, v72, v82
	v_fma_f32 v82, v72, v82, v72
	v_mul_f32_e32 v82, 0x3fcc422a, v82
	v_mul_f32_e32 v82, 0xbfb8aa3b, v82
	v_exp_f32_e32 v82, v82
	s_nop 0
	v_add_f32_e32 v82, 1.0, v82
	v_rcp_f32_e32 v82, v82
	s_nop 0
	v_mul_f32_e32 v72, v72, v82
	v_mul_f32_e32 v82, 0x3d372713, v77
	v_mul_f32_e32 v82, v77, v82
	v_fma_f32 v82, v77, v82, v77
	v_mul_f32_e32 v82, 0x3fcc422a, v82
	v_mul_f32_e32 v82, 0xbfb8aa3b, v82
	v_exp_f32_e32 v82, v82
	s_nop 0
	v_add_f32_e32 v82, 1.0, v82
	v_rcp_f32_e32 v82, v82
	s_nop 0
	v_mul_f32_e32 v77, v77, v82
	v_mul_f32_e32 v82, 0x3d372713, v73
	v_mul_f32_e32 v82, v73, v82
	v_fma_f32 v82, v73, v82, v73
	v_mul_f32_e32 v82, 0x3fcc422a, v82
	v_mul_f32_e32 v82, 0xbfb8aa3b, v82
	v_exp_f32_e32 v82, v82
	s_nop 0
	v_add_f32_e32 v82, 1.0, v82
	v_rcp_f32_e32 v82, v82
	s_nop 0
	v_mul_f32_e32 v73, v73, v82
	v_mul_f32_e32 v82, 0x3d372713, v78
	v_mul_f32_e32 v82, v78, v82
	v_fma_f32 v82, v78, v82, v78
	v_mul_f32_e32 v82, 0x3fcc422a, v82
	v_mul_f32_e32 v82, 0xbfb8aa3b, v82
	v_exp_f32_e32 v82, v82
	s_nop 0
	v_add_f32_e32 v82, 1.0, v82
	v_rcp_f32_e32 v82, v82
	s_nop 0
	v_mul_f32_e32 v78, v78, v82
	v_mul_f32_e32 v82, 0x3d372713, v74
	v_mul_f32_e32 v82, v74, v82
	v_fma_f32 v82, v74, v82, v74
	v_mul_f32_e32 v82, 0x3fcc422a, v82
	v_mul_f32_e32 v82, 0xbfb8aa3b, v82
	v_exp_f32_e32 v82, v82
	s_nop 0
	v_add_f32_e32 v82, 1.0, v82
	v_rcp_f32_e32 v82, v82
	s_nop 0
	v_mul_f32_e32 v82, v74, v82
	v_add_f32_e32 v74, v79, v103
	v_mul_f32_e32 v79, 0x3d372713, v74
	v_mul_f32_e32 v79, v74, v79
	v_fma_f32 v79, v74, v79, v74
	v_mul_f32_e32 v79, 0x3fcc422a, v79
	v_mul_f32_e32 v79, 0xbfb8aa3b, v79
	v_exp_f32_e32 v79, v79
	s_nop 0
	v_add_f32_e32 v79, 1.0, v79
	v_rcp_f32_e32 v79, v79
	s_nop 0
	v_mul_f32_e32 v79, v74, v79
	v_add_f32_e32 v74, v75, v99
	v_mul_f32_e32 v75, 0x3d372713, v74
	v_mul_f32_e32 v75, v74, v75
	v_fma_f32 v75, v74, v75, v74
	v_mul_f32_e32 v75, 0x3fcc422a, v75
	v_mul_f32_e32 v75, 0xbfb8aa3b, v75
	v_exp_f32_e32 v75, v75
	s_nop 0
	v_add_f32_e32 v75, 1.0, v75
	v_rcp_f32_e32 v75, v75
	s_nop 0
	v_mul_f32_e32 v83, v74, v75
	v_cvt_pk_bf16_f32 v74, v76, v77
	v_cvt_pk_bf16_f32 v75, v78, v79
	v_cvt_pk_bf16_f32 v76, v72, v73
	v_lshl_add_u64 v[72:73], v[132:133], 0, s[10:11]
	s_mov_b32 s10, 0x14000
	v_add_co_u32_e32 v78, vcc, s10, v132
	v_cvt_pk_bf16_f32 v77, v82, v83
	s_mov_b64 s[10:11], 0x16000
	s_nop 0
	v_addc_co_u32_e32 v79, vcc, 0, v133, vcc
	global_store_dwordx4 v[78:79], v[74:77], off sc1
	s_nop 1
	v_mul_f32_e32 v74, 0x3d372713, v68
	v_mul_f32_e32 v74, v68, v74
	v_fma_f32 v74, v68, v74, v68
	v_mul_f32_e32 v74, 0x3fcc422a, v74
	v_mul_f32_e32 v74, 0xbfb8aa3b, v74
	v_exp_f32_e32 v74, v74
	s_nop 0
	v_add_f32_e32 v74, 1.0, v74
	v_rcp_f32_e32 v74, v74
	s_nop 0
	v_mul_f32_e32 v68, v68, v74
	v_mul_f32_e32 v74, 0x3d372713, v64
	v_mul_f32_e32 v74, v64, v74
	v_fma_f32 v74, v64, v74, v64
	v_mul_f32_e32 v74, 0x3fcc422a, v74
	v_mul_f32_e32 v74, 0xbfb8aa3b, v74
	v_exp_f32_e32 v74, v74
	s_nop 0
	v_add_f32_e32 v74, 1.0, v74
	v_rcp_f32_e32 v74, v74
	s_nop 0
	v_mul_f32_e32 v74, v64, v74
	v_add_f32_e32 v64, v69, v101
	v_mul_f32_e32 v69, 0x3d372713, v64
	v_mul_f32_e32 v69, v64, v69
	v_fma_f32 v69, v64, v69, v64
	v_mul_f32_e32 v69, 0x3fcc422a, v69
	v_mul_f32_e32 v69, 0xbfb8aa3b, v69
	v_exp_f32_e32 v69, v69
	s_nop 0
	v_add_f32_e32 v69, 1.0, v69
	v_rcp_f32_e32 v69, v69
	s_nop 0
	v_mul_f32_e32 v64, v64, v69
	v_mul_f32_e32 v69, 0x3d372713, v65
; __device__ __forceinline__ float gelu_tanh(float x) { return x * sigm(1.5957691216f * (x + 0.044715f * x * x * x)); }
; __device__ __forceinline__ u32x4 pack8(f32x4 a, f32x4 b) { u32x4 o; o.x = pk2(a[0], a[1]); o.y = pk2(a[2], a[3]); o.z = pk2(b[0], b[1]); o.w = pk2(b[2], b[3]); return o; }
;     __device__ __forceinline__ void operator()(AccRef acc, const Unit& u, int wr, int wc, int fr, int fq) const {
;     ...
;         for (int bj = 0; bj < 2; ++bj) { const f32x4 b0 = *(const f32x4*)(bias + col0 + bj * 128), b1 = *(const f32x4*)(bias + col0 + bj * 128 + 4);
; #pragma unroll
;             for (int ai = 0; ai < 2; ++ai)
; #pragma unroll
;                 for (int m = 0; m < 4; ++m) { f32x4 a, b;
; #pragma unroll
;                     for (int i = 0; i < 4; ++i) { a[i] = gelu_tanh(acc[ai][bj][m][0][i] + b0[i]); b[i] = gelu_tanh(acc[ai][bj][m][1][i] + b1[i]); }
;                     *(u32x4*)(O + (size_t)(row0 + ai * 128 + m * 16) * 256 + col0 + bj * 128) = pack8(a, b); } }
	v_mul_f32_e32 v69, v65, v69
	v_fma_f32 v69, v65, v69, v65
	v_mul_f32_e32 v69, 0x3fcc422a, v69
	v_mul_f32_e32 v69, 0xbfb8aa3b, v69
	v_exp_f32_e32 v69, v69
	v_cvt_pk_bf16_f32 v64, v68, v64
	s_nop 0
	v_add_f32_e32 v69, 1.0, v69
	v_rcp_f32_e32 v69, v69
	s_nop 0
	v_mul_f32_e32 v69, v65, v69
	v_add_f32_e32 v65, v70, v102
	v_mul_f32_e32 v70, 0x3d372713, v65
	v_mul_f32_e32 v70, v65, v70
	v_fma_f32 v70, v65, v70, v65
	v_mul_f32_e32 v70, 0x3fcc422a, v70
	v_mul_f32_e32 v70, 0xbfb8aa3b, v70
	v_exp_f32_e32 v70, v70
	s_nop 0
	v_add_f32_e32 v70, 1.0, v70
	v_rcp_f32_e32 v70, v70
	s_nop 0
	v_mul_f32_e32 v65, v65, v70
	v_mul_f32_e32 v70, 0x3d372713, v66
	v_mul_f32_e32 v70, v66, v70
	v_fma_f32 v70, v66, v70, v66
	v_mul_f32_e32 v70, 0x3fcc422a, v70
	v_mul_f32_e32 v70, 0xbfb8aa3b, v70
	v_exp_f32_e32 v70, v70
	s_nop 0
	v_add_f32_e32 v70, 1.0, v70
	v_rcp_f32_e32 v70, v70
	s_nop 0
	v_mul_f32_e32 v70, v66, v70
	v_add_f32_e32 v66, v71, v103
	v_mul_f32_e32 v71, 0x3d372713, v66
	v_mul_f32_e32 v71, v66, v71
	v_fma_f32 v71, v66, v71, v66
	v_mul_f32_e32 v71, 0x3fcc422a, v71
	v_mul_f32_e32 v71, 0xbfb8aa3b, v71
	v_exp_f32_e32 v71, v71
	s_nop 0
	v_add_f32_e32 v71, 1.0, v71
	v_rcp_f32_e32 v71, v71
	s_nop 0
	v_mul_f32_e32 v66, v66, v71
	v_mul_f32_e32 v71, 0x3d372713, v67
	v_mul_f32_e32 v71, v67, v71
	v_fma_f32 v71, v67, v71, v67
	v_mul_f32_e32 v71, 0x3fcc422a, v71
	v_mul_f32_e32 v71, 0xbfb8aa3b, v71
	v_exp_f32_e32 v71, v71
	v_cvt_pk_bf16_f32 v65, v65, v66
	v_cvt_pk_bf16_f32 v66, v74, v69
	v_lshl_add_u64 v[74:75], v[132:133], 0, s[10:11]
	v_add_f32_e32 v71, 1.0, v71
	v_rcp_f32_e32 v71, v71
	s_mov_b32 s10, 0x16000
	v_add_co_u32_e32 v68, vcc, s10, v132
	v_mul_f32_e32 v67, v67, v71
	s_nop 0
	v_addc_co_u32_e32 v69, vcc, 0, v133, vcc
	v_cvt_pk_bf16_f32 v67, v70, v67
	global_store_dwordx4 v[68:69], v[64:67], off sc1
	global_load_dwordx4 v[64:67], v[144:145], off offset:528
	s_nop 0
	global_load_dwordx4 v[68:71], v[144:145], off offset:512
	s_andn2_b64 vcc, exec, s[8:9]
	s_waitcnt vmcnt(1)
	v_add_f32_e32 v56, v56, v64
	s_waitcnt vmcnt(0)
	v_add_f32_e32 v60, v60, v68
	v_mul_f32_e32 v76, 0x3d372713, v60
	v_mul_f32_e32 v76, v60, v76
	v_fma_f32 v76, v60, v76, v60
	v_mul_f32_e32 v76, 0x3fcc422a, v76
	v_mul_f32_e32 v76, 0xbfb8aa3b, v76
	v_exp_f32_e32 v76, v76
	v_add_f32_e32 v57, v57, v65
	v_add_f32_e32 v58, v58, v66
	v_add_f32_e32 v59, v59, v67
	v_add_f32_e32 v76, 1.0, v76
	v_rcp_f32_e32 v76, v76
	v_add_f32_e32 v52, v52, v68
	v_add_f32_e32 v48, v48, v64
	v_add_f32_e32 v49, v49, v65
	v_mul_f32_e32 v60, v60, v76
	v_mul_f32_e32 v76, 0x3d372713, v56
	v_mul_f32_e32 v76, v56, v76
	v_fma_f32 v76, v56, v76, v56
	v_mul_f32_e32 v76, 0x3fcc422a, v76
	v_mul_f32_e32 v76, 0xbfb8aa3b, v76
	v_exp_f32_e32 v76, v76
	v_add_f32_e32 v50, v50, v66
	v_add_f32_e32 v51, v51, v67
	v_add_f32_e32 v44, v44, v68
	v_add_f32_e32 v76, 1.0, v76
	v_rcp_f32_e32 v76, v76
	v_add_f32_e32 v40, v40, v64
	v_add_f32_e32 v41, v41, v65
	v_add_f32_e32 v42, v42, v66
	v_mul_f32_e32 v76, v56, v76
	v_add_f32_e32 v56, v61, v69
	v_mul_f32_e32 v61, 0x3d372713, v56
	v_mul_f32_e32 v61, v56, v61
	v_fma_f32 v61, v56, v61, v56
	v_mul_f32_e32 v61, 0x3fcc422a, v61
	v_mul_f32_e32 v61, 0xbfb8aa3b, v61
	v_exp_f32_e32 v61, v61
	v_add_f32_e32 v43, v43, v67
	v_add_f32_e32 v36, v36, v68
	v_add_f32_e32 v32, v32, v64
	v_add_f32_e32 v61, 1.0, v61
	v_rcp_f32_e32 v61, v61
	v_add_f32_e32 v33, v33, v65
	v_add_f32_e32 v34, v34, v66
	v_add_f32_e32 v35, v35, v67
	v_mul_f32_e32 v56, v56, v61
	v_mul_f32_e32 v61, 0x3d372713, v57
	v_mul_f32_e32 v61, v57, v61
	v_fma_f32 v61, v57, v61, v57
	v_mul_f32_e32 v61, 0x3fcc422a, v61
	v_mul_f32_e32 v61, 0xbfb8aa3b, v61
	v_exp_f32_e32 v61, v61
	v_cvt_pk_bf16_f32 v56, v60, v56
	v_add_f32_e32 v28, v28, v68
	v_add_f32_e32 v24, v24, v64
	v_add_f32_e32 v61, 1.0, v61
	v_rcp_f32_e32 v61, v61
	v_add_f32_e32 v25, v25, v65
	v_add_f32_e32 v26, v26, v66
	v_add_f32_e32 v27, v27, v67
	v_mul_f32_e32 v61, v57, v61
	v_add_f32_e32 v57, v62, v70
	v_mul_f32_e32 v62, 0x3d372713, v57
	v_mul_f32_e32 v62, v57, v62
	v_fma_f32 v62, v57, v62, v57
	v_mul_f32_e32 v62, 0x3fcc422a, v62
	v_mul_f32_e32 v62, 0xbfb8aa3b, v62
	v_exp_f32_e32 v62, v62
	v_add_f32_e32 v20, v20, v68
	v_add_f32_e32 v16, v16, v64
	v_add_f32_e32 v17, v17, v65
	v_add_f32_e32 v62, 1.0, v62
	v_rcp_f32_e32 v62, v62
	v_add_f32_e32 v18, v18, v66
	v_add_f32_e32 v19, v19, v67
	v_add_f32_e32 v12, v12, v68
	v_mul_f32_e32 v57, v57, v62
	v_mul_f32_e32 v62, 0x3d372713, v58
	v_mul_f32_e32 v62, v58, v62
	v_fma_f32 v62, v58, v62, v58
	v_mul_f32_e32 v62, 0x3fcc422a, v62
	v_mul_f32_e32 v62, 0xbfb8aa3b, v62
	v_exp_f32_e32 v62, v62
	v_add_f32_e32 v8, v8, v64
	v_add_f32_e32 v9, v9, v65
	v_add_f32_e32 v10, v10, v66
	v_add_f32_e32 v62, 1.0, v62
	v_rcp_f32_e32 v62, v62
	v_add_f32_e32 v11, v11, v67
	v_add_f32_e32 v4, v4, v68
	v_add_f32_e32 v0, v0, v64
	v_mul_f32_e32 v62, v58, v62
	v_add_f32_e32 v58, v63, v71
	v_mul_f32_e32 v63, 0x3d372713, v58
	v_mul_f32_e32 v63, v58, v63
	v_fma_f32 v63, v58, v63, v58
	v_mul_f32_e32 v63, 0x3fcc422a, v63
	v_mul_f32_e32 v63, 0xbfb8aa3b, v63
	v_exp_f32_e32 v63, v63
	v_add_f32_e32 v1, v1, v65
	v_add_f32_e32 v2, v2, v66
	v_add_f32_e32 v3, v3, v67
	v_add_f32_e32 v63, 1.0, v63
	v_rcp_f32_e32 v63, v63
	s_nop 0
	v_mul_f32_e32 v58, v58, v63
	v_mul_f32_e32 v63, 0x3d372713, v59
	v_mul_f32_e32 v63, v59, v63
	v_fma_f32 v63, v59, v63, v59
	v_mul_f32_e32 v63, 0x3fcc422a, v63
	v_mul_f32_e32 v63, 0xbfb8aa3b, v63
	v_exp_f32_e32 v63, v63
	v_cvt_pk_bf16_f32 v57, v57, v58
	v_cvt_pk_bf16_f32 v58, v76, v61
	s_nop 0
	v_add_f32_e32 v63, 1.0, v63
	v_rcp_f32_e32 v63, v63
	s_nop 0
	v_mul_f32_e32 v59, v59, v63
	v_cvt_pk_bf16_f32 v59, v62, v59
	global_store_dwordx4 v[132:133], v[56:59], off offset:256 sc1
; __device__ __forceinline__ float gelu_tanh(float x) { return x * sigm(1.5957691216f * (x + 0.044715f * x * x * x)); }
; __device__ __forceinline__ u32x4 pack8(f32x4 a, f32x4 b) { u32x4 o; o.x = pk2(a[0], a[1]); o.y = pk2(a[2], a[3]); o.z = pk2(b[0], b[1]); o.w = pk2(b[2], b[3]); return o; }
;     __device__ __forceinline__ void operator()(AccRef acc, const Unit& u, int wr, int wc, int fr, int fq) const {
;     ...
;         for (int bj = 0; bj < 2; ++bj) { const f32x4 b0 = *(const f32x4*)(bias + col0 + bj * 128), b1 = *(const f32x4*)(bias + col0 + bj * 128 + 4);
; #pragma unroll
;             for (int ai = 0; ai < 2; ++ai)
; #pragma unroll
;                 for (int m = 0; m < 4; ++m) { f32x4 a, b;
; #pragma unroll
;                     for (int i = 0; i < 4; ++i) { a[i] = gelu_tanh(acc[ai][bj][m][0][i] + b0[i]); b[i] = gelu_tanh(acc[ai][bj][m][1][i] + b1[i]); }
;                     *(u32x4*)(O + (size_t)(row0 + ai * 128 + m * 16) * 256 + col0 + bj * 128) = pack8(a, b); } }
	s_nop 1
	v_mul_f32_e32 v56, 0x3d372713, v52
	v_mul_f32_e32 v56, v52, v56
	v_fma_f32 v56, v52, v56, v52
	v_mul_f32_e32 v56, 0x3fcc422a, v56
	v_mul_f32_e32 v56, 0xbfb8aa3b, v56
	v_exp_f32_e32 v56, v56
	s_nop 0
	v_add_f32_e32 v56, 1.0, v56
	v_rcp_f32_e32 v56, v56
	s_nop 0
	v_mul_f32_e32 v52, v52, v56
	v_mul_f32_e32 v56, 0x3d372713, v48
	v_mul_f32_e32 v56, v48, v56
	v_fma_f32 v56, v48, v56, v48
	v_mul_f32_e32 v56, 0x3fcc422a, v56
	v_mul_f32_e32 v56, 0xbfb8aa3b, v56
	v_exp_f32_e32 v56, v56
	s_nop 0
	v_add_f32_e32 v56, 1.0, v56
	v_rcp_f32_e32 v56, v56
	s_nop 0
	v_mul_f32_e32 v56, v48, v56
	v_add_f32_e32 v48, v53, v69
	v_mul_f32_e32 v53, 0x3d372713, v48
	v_mul_f32_e32 v53, v48, v53
	v_fma_f32 v53, v48, v53, v48
	v_mul_f32_e32 v53, 0x3fcc422a, v53
	v_mul_f32_e32 v53, 0xbfb8aa3b, v53
	v_exp_f32_e32 v53, v53
	s_nop 0
	v_add_f32_e32 v53, 1.0, v53
	v_rcp_f32_e32 v53, v53
	s_nop 0
	v_mul_f32_e32 v48, v48, v53
	v_mul_f32_e32 v53, 0x3d372713, v49
	v_mul_f32_e32 v53, v49, v53
	v_fma_f32 v53, v49, v53, v49
	v_mul_f32_e32 v53, 0x3fcc422a, v53
	v_mul_f32_e32 v53, 0xbfb8aa3b, v53
	v_exp_f32_e32 v53, v53
	v_cvt_pk_bf16_f32 v48, v52, v48
	s_nop 0
	v_add_f32_e32 v53, 1.0, v53
	v_rcp_f32_e32 v53, v53
	s_nop 0
	v_mul_f32_e32 v53, v49, v53
	v_add_f32_e32 v49, v54, v70
	v_mul_f32_e32 v54, 0x3d372713, v49
	v_mul_f32_e32 v54, v49, v54
	v_fma_f32 v54, v49, v54, v49
	v_mul_f32_e32 v54, 0x3fcc422a, v54
	v_mul_f32_e32 v54, 0xbfb8aa3b, v54
	v_exp_f32_e32 v54, v54
	s_nop 0
	v_add_f32_e32 v54, 1.0, v54
	v_rcp_f32_e32 v54, v54
	s_nop 0
	v_mul_f32_e32 v49, v49, v54
	v_mul_f32_e32 v54, 0x3d372713, v50
	v_mul_f32_e32 v54, v50, v54
	v_fma_f32 v54, v50, v54, v50
	v_mul_f32_e32 v54, 0x3fcc422a, v54
	v_mul_f32_e32 v54, 0xbfb8aa3b, v54
	v_exp_f32_e32 v54, v54
	s_nop 0
	v_add_f32_e32 v54, 1.0, v54
	v_rcp_f32_e32 v54, v54
	s_nop 0
	v_mul_f32_e32 v54, v50, v54
	v_add_f32_e32 v50, v55, v71
	v_mul_f32_e32 v55, 0x3d372713, v50
	v_mul_f32_e32 v55, v50, v55
	v_fma_f32 v55, v50, v55, v50
	v_mul_f32_e32 v55, 0x3fcc422a, v55
	v_mul_f32_e32 v55, 0xbfb8aa3b, v55
	v_exp_f32_e32 v55, v55
	s_nop 0
	v_add_f32_e32 v55, 1.0, v55
	v_rcp_f32_e32 v55, v55
	s_nop 0
	v_mul_f32_e32 v50, v50, v55
	v_mul_f32_e32 v55, 0x3d372713, v51
	v_mul_f32_e32 v55, v51, v55
	v_fma_f32 v55, v51, v55, v51
	v_mul_f32_e32 v55, 0x3fcc422a, v55
	v_mul_f32_e32 v55, 0xbfb8aa3b, v55
	v_exp_f32_e32 v55, v55
	v_cvt_pk_bf16_f32 v49, v49, v50
	v_cvt_pk_bf16_f32 v50, v56, v53
	s_nop 0
	v_add_f32_e32 v55, 1.0, v55
	v_rcp_f32_e32 v55, v55
	s_nop 0
	v_mul_f32_e32 v51, v51, v55
	v_cvt_pk_bf16_f32 v51, v54, v51
	global_store_dwordx4 v[120:121], v[48:51], off offset:256 sc1
	s_nop 1
	v_mul_f32_e32 v48, 0x3d372713, v44
	v_mul_f32_e32 v48, v44, v48
	v_fma_f32 v48, v44, v48, v44
	v_mul_f32_e32 v48, 0x3fcc422a, v48
	v_mul_f32_e32 v48, 0xbfb8aa3b, v48
	v_exp_f32_e32 v48, v48
	s_nop 0
	v_add_f32_e32 v48, 1.0, v48
	v_rcp_f32_e32 v48, v48
	s_nop 0
	v_mul_f32_e32 v44, v44, v48
	v_mul_f32_e32 v48, 0x3d372713, v40
	v_mul_f32_e32 v48, v40, v48
	v_fma_f32 v48, v40, v48, v40
	v_mul_f32_e32 v48, 0x3fcc422a, v48
	v_mul_f32_e32 v48, 0xbfb8aa3b, v48
	v_exp_f32_e32 v48, v48
	s_nop 0
	v_add_f32_e32 v48, 1.0, v48
	v_rcp_f32_e32 v48, v48
	s_nop 0
	v_mul_f32_e32 v48, v40, v48
	v_add_f32_e32 v40, v45, v69
	v_mul_f32_e32 v45, 0x3d372713, v40
	v_mul_f32_e32 v45, v40, v45
	v_fma_f32 v45, v40, v45, v40
	v_mul_f32_e32 v45, 0x3fcc422a, v45
	v_mul_f32_e32 v45, 0xbfb8aa3b, v45
	v_exp_f32_e32 v45, v45
	s_nop 0
	v_add_f32_e32 v45, 1.0, v45
	v_rcp_f32_e32 v45, v45
	s_nop 0
	v_mul_f32_e32 v40, v40, v45
	v_mul_f32_e32 v45, 0x3d372713, v41
	v_mul_f32_e32 v45, v41, v45
	v_fma_f32 v45, v41, v45, v41
	v_mul_f32_e32 v45, 0x3fcc422a, v45
	v_mul_f32_e32 v45, 0xbfb8aa3b, v45
	v_exp_f32_e32 v45, v45
	v_cvt_pk_bf16_f32 v40, v44, v40
	s_nop 0
	v_add_f32_e32 v45, 1.0, v45
	v_rcp_f32_e32 v45, v45
	s_nop 0
	v_mul_f32_e32 v45, v41, v45
	v_add_f32_e32 v41, v46, v70
	v_mul_f32_e32 v46, 0x3d372713, v41
	v_mul_f32_e32 v46, v41, v46
	v_fma_f32 v46, v41, v46, v41
	v_mul_f32_e32 v46, 0x3fcc422a, v46
	v_mul_f32_e32 v46, 0xbfb8aa3b, v46
	v_exp_f32_e32 v46, v46
	s_nop 0
	v_add_f32_e32 v46, 1.0, v46
	v_rcp_f32_e32 v46, v46
	s_nop 0
	v_mul_f32_e32 v41, v41, v46
	v_mul_f32_e32 v46, 0x3d372713, v42
	v_mul_f32_e32 v46, v42, v46
	v_fma_f32 v46, v42, v46, v42
	v_mul_f32_e32 v46, 0x3fcc422a, v46
	v_mul_f32_e32 v46, 0xbfb8aa3b, v46
	v_exp_f32_e32 v46, v46
	s_nop 0
	v_add_f32_e32 v46, 1.0, v46
	v_rcp_f32_e32 v46, v46
	s_nop 0
	v_mul_f32_e32 v46, v42, v46
	v_add_f32_e32 v42, v47, v71
	v_mul_f32_e32 v47, 0x3d372713, v42
	v_mul_f32_e32 v47, v42, v47
	v_fma_f32 v47, v42, v47, v42
	v_mul_f32_e32 v47, 0x3fcc422a, v47
	v_mul_f32_e32 v47, 0xbfb8aa3b, v47
	v_exp_f32_e32 v47, v47
	s_nop 0
	v_add_f32_e32 v47, 1.0, v47
	v_rcp_f32_e32 v47, v47
	s_nop 0
	v_mul_f32_e32 v42, v42, v47
	v_mul_f32_e32 v47, 0x3d372713, v43
	v_mul_f32_e32 v47, v43, v47
	v_fma_f32 v47, v43, v47, v43
	v_mul_f32_e32 v47, 0x3fcc422a, v47
	v_mul_f32_e32 v47, 0xbfb8aa3b, v47
	v_exp_f32_e32 v47, v47
	v_cvt_pk_bf16_f32 v41, v41, v42
	v_cvt_pk_bf16_f32 v42, v48, v45
	s_nop 0
	v_add_f32_e32 v47, 1.0, v47
	v_rcp_f32_e32 v47, v47
	s_nop 0
	v_mul_f32_e32 v43, v43, v47
	v_cvt_pk_bf16_f32 v43, v46, v43
	global_store_dwordx4 v[112:113], v[40:43], off offset:256 sc1
	s_nop 1
	v_mul_f32_e32 v40, 0x3d372713, v36
	v_mul_f32_e32 v40, v36, v40
	v_fma_f32 v40, v36, v40, v36
	v_mul_f32_e32 v40, 0x3fcc422a, v40
	v_mul_f32_e32 v40, 0xbfb8aa3b, v40
	v_exp_f32_e32 v40, v40
	s_nop 0
	v_add_f32_e32 v40, 1.0, v40
	v_rcp_f32_e32 v40, v40
	s_nop 0
	v_mul_f32_e32 v36, v36, v40
	v_mul_f32_e32 v40, 0x3d372713, v32
	v_mul_f32_e32 v40, v32, v40
	v_fma_f32 v40, v32, v40, v32
; __device__ __forceinline__ float gelu_tanh(float x) { return x * sigm(1.5957691216f * (x + 0.044715f * x * x * x)); }
; __device__ __forceinline__ u32x4 pack8(f32x4 a, f32x4 b) { u32x4 o; o.x = pk2(a[0], a[1]); o.y = pk2(a[2], a[3]); o.z = pk2(b[0], b[1]); o.w = pk2(b[2], b[3]); return o; }
;     __device__ __forceinline__ void operator()(AccRef acc, const Unit& u, int wr, int wc, int fr, int fq) const {
;     ...
;         for (int bj = 0; bj < 2; ++bj) { const f32x4 b0 = *(const f32x4*)(bias + col0 + bj * 128), b1 = *(const f32x4*)(bias + col0 + bj * 128 + 4);
; #pragma unroll
;             for (int ai = 0; ai < 2; ++ai)
; #pragma unroll
;                 for (int m = 0; m < 4; ++m) { f32x4 a, b;
; #pragma unroll
;                     for (int i = 0; i < 4; ++i) { a[i] = gelu_tanh(acc[ai][bj][m][0][i] + b0[i]); b[i] = gelu_tanh(acc[ai][bj][m][1][i] + b1[i]); }
;                     *(u32x4*)(O + (size_t)(row0 + ai * 128 + m * 16) * 256 + col0 + bj * 128) = pack8(a, b); } }
	v_mul_f32_e32 v40, 0x3fcc422a, v40
	v_mul_f32_e32 v40, 0xbfb8aa3b, v40
	v_exp_f32_e32 v40, v40
	s_nop 0
	v_add_f32_e32 v40, 1.0, v40
	v_rcp_f32_e32 v40, v40
	s_nop 0
	v_mul_f32_e32 v40, v32, v40
	v_add_f32_e32 v32, v37, v69
	v_mul_f32_e32 v37, 0x3d372713, v32
	v_mul_f32_e32 v37, v32, v37
	v_fma_f32 v37, v32, v37, v32
	v_mul_f32_e32 v37, 0x3fcc422a, v37
	v_mul_f32_e32 v37, 0xbfb8aa3b, v37
	v_exp_f32_e32 v37, v37
	s_nop 0
	v_add_f32_e32 v37, 1.0, v37
	v_rcp_f32_e32 v37, v37
	s_nop 0
	v_mul_f32_e32 v32, v32, v37
	v_mul_f32_e32 v37, 0x3d372713, v33
	v_mul_f32_e32 v37, v33, v37
	v_fma_f32 v37, v33, v37, v33
	v_mul_f32_e32 v37, 0x3fcc422a, v37
	v_mul_f32_e32 v37, 0xbfb8aa3b, v37
	v_exp_f32_e32 v37, v37
	v_cvt_pk_bf16_f32 v32, v36, v32
	s_nop 0
	v_add_f32_e32 v37, 1.0, v37
	v_rcp_f32_e32 v37, v37
	s_nop 0
	v_mul_f32_e32 v37, v33, v37
	v_add_f32_e32 v33, v38, v70
	v_mul_f32_e32 v38, 0x3d372713, v33
	v_mul_f32_e32 v38, v33, v38
	v_fma_f32 v38, v33, v38, v33
	v_mul_f32_e32 v38, 0x3fcc422a, v38
	v_mul_f32_e32 v38, 0xbfb8aa3b, v38
	v_exp_f32_e32 v38, v38
	s_nop 0
	v_add_f32_e32 v38, 1.0, v38
	v_rcp_f32_e32 v38, v38
	s_nop 0
	v_mul_f32_e32 v33, v33, v38
	v_mul_f32_e32 v38, 0x3d372713, v34
	v_mul_f32_e32 v38, v34, v38
	v_fma_f32 v38, v34, v38, v34
	v_mul_f32_e32 v38, 0x3fcc422a, v38
	v_mul_f32_e32 v38, 0xbfb8aa3b, v38
	v_exp_f32_e32 v38, v38
	s_nop 0
	v_add_f32_e32 v38, 1.0, v38
	v_rcp_f32_e32 v38, v38
	s_nop 0
	v_mul_f32_e32 v38, v34, v38
	v_add_f32_e32 v34, v39, v71
	v_mul_f32_e32 v39, 0x3d372713, v34
	v_mul_f32_e32 v39, v34, v39
	v_fma_f32 v39, v34, v39, v34
	v_mul_f32_e32 v39, 0x3fcc422a, v39
	v_mul_f32_e32 v39, 0xbfb8aa3b, v39
	v_exp_f32_e32 v39, v39
	s_nop 0
	v_add_f32_e32 v39, 1.0, v39
	v_rcp_f32_e32 v39, v39
	s_nop 0
	v_mul_f32_e32 v34, v34, v39
	v_mul_f32_e32 v39, 0x3d372713, v35
	v_mul_f32_e32 v39, v35, v39
	v_fma_f32 v39, v35, v39, v35
	v_mul_f32_e32 v39, 0x3fcc422a, v39
	v_mul_f32_e32 v39, 0xbfb8aa3b, v39
	v_exp_f32_e32 v39, v39
	v_cvt_pk_bf16_f32 v33, v33, v34
	v_cvt_pk_bf16_f32 v34, v40, v37
	s_nop 0
	v_add_f32_e32 v39, 1.0, v39
	v_rcp_f32_e32 v39, v39
	s_nop 0
	v_mul_f32_e32 v35, v35, v39
	v_cvt_pk_bf16_f32 v35, v38, v35
	global_store_dwordx4 v[104:105], v[32:35], off offset:256 sc1
	s_nop 1
	v_mul_f32_e32 v32, 0x3d372713, v28
	v_mul_f32_e32 v32, v28, v32
	v_fma_f32 v32, v28, v32, v28
	v_mul_f32_e32 v32, 0x3fcc422a, v32
	v_mul_f32_e32 v32, 0xbfb8aa3b, v32
	v_exp_f32_e32 v32, v32
	s_nop 0
	v_add_f32_e32 v32, 1.0, v32
	v_rcp_f32_e32 v32, v32
	s_nop 0
	v_mul_f32_e32 v28, v28, v32
	v_mul_f32_e32 v32, 0x3d372713, v24
	v_mul_f32_e32 v32, v24, v32
	v_fma_f32 v32, v24, v32, v24
	v_mul_f32_e32 v32, 0x3fcc422a, v32
	v_mul_f32_e32 v32, 0xbfb8aa3b, v32
	v_exp_f32_e32 v32, v32
	s_nop 0
	v_add_f32_e32 v32, 1.0, v32
	v_rcp_f32_e32 v32, v32
	s_nop 0
	v_mul_f32_e32 v32, v24, v32
	v_add_f32_e32 v24, v29, v69
	v_mul_f32_e32 v29, 0x3d372713, v24
	v_mul_f32_e32 v29, v24, v29
	v_fma_f32 v29, v24, v29, v24
	v_mul_f32_e32 v29, 0x3fcc422a, v29
	v_mul_f32_e32 v29, 0xbfb8aa3b, v29
	v_exp_f32_e32 v29, v29
	s_nop 0
	v_add_f32_e32 v29, 1.0, v29
	v_rcp_f32_e32 v29, v29
	s_nop 0
	v_mul_f32_e32 v24, v24, v29
	v_mul_f32_e32 v29, 0x3d372713, v25
	v_mul_f32_e32 v29, v25, v29
	v_fma_f32 v29, v25, v29, v25
	v_mul_f32_e32 v29, 0x3fcc422a, v29
	v_mul_f32_e32 v29, 0xbfb8aa3b, v29
	v_exp_f32_e32 v29, v29
	v_cvt_pk_bf16_f32 v24, v28, v24
	s_nop 0
	v_add_f32_e32 v29, 1.0, v29
	v_rcp_f32_e32 v29, v29
	s_nop 0
	v_mul_f32_e32 v29, v25, v29
	v_add_f32_e32 v25, v30, v70
	v_mul_f32_e32 v30, 0x3d372713, v25
	v_mul_f32_e32 v30, v25, v30
	v_fma_f32 v30, v25, v30, v25
	v_mul_f32_e32 v30, 0x3fcc422a, v30
	v_mul_f32_e32 v30, 0xbfb8aa3b, v30
	v_exp_f32_e32 v30, v30
	s_nop 0
	v_add_f32_e32 v30, 1.0, v30
	v_rcp_f32_e32 v30, v30
	s_nop 0
	v_mul_f32_e32 v25, v25, v30
	v_mul_f32_e32 v30, 0x3d372713, v26
	v_mul_f32_e32 v30, v26, v30
	v_fma_f32 v30, v26, v30, v26
	v_mul_f32_e32 v30, 0x3fcc422a, v30
	v_mul_f32_e32 v30, 0xbfb8aa3b, v30
	v_exp_f32_e32 v30, v30
	s_nop 0
	v_add_f32_e32 v30, 1.0, v30
	v_rcp_f32_e32 v30, v30
	s_nop 0
	v_mul_f32_e32 v30, v26, v30
	v_add_f32_e32 v26, v31, v71
	v_mul_f32_e32 v31, 0x3d372713, v26
	v_mul_f32_e32 v31, v26, v31
	v_fma_f32 v31, v26, v31, v26
	v_mul_f32_e32 v31, 0x3fcc422a, v31
	v_mul_f32_e32 v31, 0xbfb8aa3b, v31
	v_exp_f32_e32 v31, v31
	s_nop 0
	v_add_f32_e32 v31, 1.0, v31
	v_rcp_f32_e32 v31, v31
	s_nop 0
	v_mul_f32_e32 v26, v26, v31
	v_mul_f32_e32 v31, 0x3d372713, v27
	v_mul_f32_e32 v31, v27, v31
	v_fma_f32 v31, v27, v31, v27
	v_mul_f32_e32 v31, 0x3fcc422a, v31
	v_mul_f32_e32 v31, 0xbfb8aa3b, v31
	v_exp_f32_e32 v31, v31
	v_cvt_pk_bf16_f32 v25, v25, v26
	v_cvt_pk_bf16_f32 v26, v32, v29
	s_nop 0
	v_add_f32_e32 v31, 1.0, v31
	v_rcp_f32_e32 v31, v31
	s_nop 0
	v_mul_f32_e32 v27, v27, v31
	v_cvt_pk_bf16_f32 v27, v30, v27
	global_store_dwordx4 v[88:89], v[24:27], off offset:256 sc1
	s_nop 1
	v_mul_f32_e32 v24, 0x3d372713, v20
	v_mul_f32_e32 v24, v20, v24
	v_fma_f32 v24, v20, v24, v20
	v_mul_f32_e32 v24, 0x3fcc422a, v24
	v_mul_f32_e32 v24, 0xbfb8aa3b, v24
	v_exp_f32_e32 v24, v24
	s_nop 0
	v_add_f32_e32 v24, 1.0, v24
	v_rcp_f32_e32 v24, v24
	s_nop 0
	v_mul_f32_e32 v20, v20, v24
	v_mul_f32_e32 v24, 0x3d372713, v16
	v_mul_f32_e32 v24, v16, v24
	v_fma_f32 v24, v16, v24, v16
	v_mul_f32_e32 v24, 0x3fcc422a, v24
	v_mul_f32_e32 v24, 0xbfb8aa3b, v24
	v_exp_f32_e32 v24, v24
	s_nop 0
	v_add_f32_e32 v24, 1.0, v24
	v_rcp_f32_e32 v24, v24
	s_nop 0
	v_mul_f32_e32 v24, v16, v24
	v_add_f32_e32 v16, v21, v69
	v_mul_f32_e32 v21, 0x3d372713, v16
	v_mul_f32_e32 v21, v16, v21
	v_fma_f32 v21, v16, v21, v16
	v_mul_f32_e32 v21, 0x3fcc422a, v21
	v_mul_f32_e32 v21, 0xbfb8aa3b, v21
; __device__ __forceinline__ float gelu_tanh(float x) { return x * sigm(1.5957691216f * (x + 0.044715f * x * x * x)); }
; __device__ __forceinline__ u32x4 pack8(f32x4 a, f32x4 b) { u32x4 o; o.x = pk2(a[0], a[1]); o.y = pk2(a[2], a[3]); o.z = pk2(b[0], b[1]); o.w = pk2(b[2], b[3]); return o; }
;     __device__ __forceinline__ void operator()(AccRef acc, const Unit& u, int wr, int wc, int fr, int fq) const {
;     ...
;         for (int bj = 0; bj < 2; ++bj) { const f32x4 b0 = *(const f32x4*)(bias + col0 + bj * 128), b1 = *(const f32x4*)(bias + col0 + bj * 128 + 4);
; #pragma unroll
;             for (int ai = 0; ai < 2; ++ai)
; #pragma unroll
;                 for (int m = 0; m < 4; ++m) { f32x4 a, b;
; #pragma unroll
;                     for (int i = 0; i < 4; ++i) { a[i] = gelu_tanh(acc[ai][bj][m][0][i] + b0[i]); b[i] = gelu_tanh(acc[ai][bj][m][1][i] + b1[i]); }
;                     *(u32x4*)(O + (size_t)(row0 + ai * 128 + m * 16) * 256 + col0 + bj * 128) = pack8(a, b); } }
	v_exp_f32_e32 v21, v21
	s_nop 0
	v_add_f32_e32 v21, 1.0, v21
	v_rcp_f32_e32 v21, v21
	s_nop 0
	v_mul_f32_e32 v16, v16, v21
	v_mul_f32_e32 v21, 0x3d372713, v17
	v_mul_f32_e32 v21, v17, v21
	v_fma_f32 v21, v17, v21, v17
	v_mul_f32_e32 v21, 0x3fcc422a, v21
	v_mul_f32_e32 v21, 0xbfb8aa3b, v21
	v_exp_f32_e32 v21, v21
	v_cvt_pk_bf16_f32 v16, v20, v16
	s_nop 0
	v_add_f32_e32 v21, 1.0, v21
	v_rcp_f32_e32 v21, v21
	s_nop 0
	v_mul_f32_e32 v21, v17, v21
	v_add_f32_e32 v17, v22, v70
	v_mul_f32_e32 v22, 0x3d372713, v17
	v_mul_f32_e32 v22, v17, v22
	v_fma_f32 v22, v17, v22, v17
	v_mul_f32_e32 v22, 0x3fcc422a, v22
	v_mul_f32_e32 v22, 0xbfb8aa3b, v22
	v_exp_f32_e32 v22, v22
	s_nop 0
	v_add_f32_e32 v22, 1.0, v22
	v_rcp_f32_e32 v22, v22
	s_nop 0
	v_mul_f32_e32 v17, v17, v22
	v_mul_f32_e32 v22, 0x3d372713, v18
	v_mul_f32_e32 v22, v18, v22
	v_fma_f32 v22, v18, v22, v18
	v_mul_f32_e32 v22, 0x3fcc422a, v22
	v_mul_f32_e32 v22, 0xbfb8aa3b, v22
	v_exp_f32_e32 v22, v22
	s_nop 0
	v_add_f32_e32 v22, 1.0, v22
	v_rcp_f32_e32 v22, v22
	s_nop 0
	v_mul_f32_e32 v22, v18, v22
	v_add_f32_e32 v18, v23, v71
	v_mul_f32_e32 v23, 0x3d372713, v18
	v_mul_f32_e32 v23, v18, v23
	v_fma_f32 v23, v18, v23, v18
	v_mul_f32_e32 v23, 0x3fcc422a, v23
	v_mul_f32_e32 v23, 0xbfb8aa3b, v23
	v_exp_f32_e32 v23, v23
	s_nop 0
	v_add_f32_e32 v23, 1.0, v23
	v_rcp_f32_e32 v23, v23
	s_nop 0
	v_mul_f32_e32 v18, v18, v23
	v_mul_f32_e32 v23, 0x3d372713, v19
	v_mul_f32_e32 v23, v19, v23
	v_fma_f32 v23, v19, v23, v19
	v_mul_f32_e32 v23, 0x3fcc422a, v23
	v_mul_f32_e32 v23, 0xbfb8aa3b, v23
	v_exp_f32_e32 v23, v23
	v_cvt_pk_bf16_f32 v17, v17, v18
	v_cvt_pk_bf16_f32 v18, v24, v21
	s_nop 0
	v_add_f32_e32 v23, 1.0, v23
	v_rcp_f32_e32 v23, v23
	s_nop 0
	v_mul_f32_e32 v19, v19, v23
	v_cvt_pk_bf16_f32 v19, v22, v19
	global_store_dwordx4 v[80:81], v[16:19], off offset:256 sc1
	s_nop 1
	v_mul_f32_e32 v16, 0x3d372713, v12
	v_mul_f32_e32 v16, v12, v16
	v_fma_f32 v16, v12, v16, v12
	v_mul_f32_e32 v16, 0x3fcc422a, v16
	v_mul_f32_e32 v16, 0xbfb8aa3b, v16
	v_exp_f32_e32 v16, v16
	s_nop 0
	v_add_f32_e32 v16, 1.0, v16
	v_rcp_f32_e32 v16, v16
	s_nop 0
	v_mul_f32_e32 v12, v12, v16
	v_mul_f32_e32 v16, 0x3d372713, v8
	v_mul_f32_e32 v16, v8, v16
	v_fma_f32 v16, v8, v16, v8
	v_mul_f32_e32 v16, 0x3fcc422a, v16
	v_mul_f32_e32 v16, 0xbfb8aa3b, v16
	v_exp_f32_e32 v16, v16
	s_nop 0
	v_add_f32_e32 v16, 1.0, v16
	v_rcp_f32_e32 v16, v16
	s_nop 0
	v_mul_f32_e32 v16, v8, v16
	v_add_f32_e32 v8, v13, v69
	v_mul_f32_e32 v13, 0x3d372713, v8
	v_mul_f32_e32 v13, v8, v13
	v_fma_f32 v13, v8, v13, v8
	v_mul_f32_e32 v13, 0x3fcc422a, v13
	v_mul_f32_e32 v13, 0xbfb8aa3b, v13
	v_exp_f32_e32 v13, v13
	s_nop 0
	v_add_f32_e32 v13, 1.0, v13
	v_rcp_f32_e32 v13, v13
	s_nop 0
	v_mul_f32_e32 v8, v8, v13
	v_mul_f32_e32 v13, 0x3d372713, v9
	v_mul_f32_e32 v13, v9, v13
	v_fma_f32 v13, v9, v13, v9
	v_mul_f32_e32 v13, 0x3fcc422a, v13
	v_mul_f32_e32 v13, 0xbfb8aa3b, v13
	v_exp_f32_e32 v13, v13
	v_cvt_pk_bf16_f32 v8, v12, v8
	s_nop 0
	v_add_f32_e32 v13, 1.0, v13
	v_rcp_f32_e32 v13, v13
	s_nop 0
	v_mul_f32_e32 v13, v9, v13
	v_add_f32_e32 v9, v14, v70
	v_mul_f32_e32 v14, 0x3d372713, v9
	v_mul_f32_e32 v14, v9, v14
	v_fma_f32 v14, v9, v14, v9
	v_mul_f32_e32 v14, 0x3fcc422a, v14
	v_mul_f32_e32 v14, 0xbfb8aa3b, v14
	v_exp_f32_e32 v14, v14
	s_nop 0
	v_add_f32_e32 v14, 1.0, v14
	v_rcp_f32_e32 v14, v14
	s_nop 0
	v_mul_f32_e32 v9, v9, v14
	v_mul_f32_e32 v14, 0x3d372713, v10
	v_mul_f32_e32 v14, v10, v14
	v_fma_f32 v14, v10, v14, v10
	v_mul_f32_e32 v14, 0x3fcc422a, v14
	v_mul_f32_e32 v14, 0xbfb8aa3b, v14
	v_exp_f32_e32 v14, v14
	s_nop 0
	v_add_f32_e32 v14, 1.0, v14
	v_rcp_f32_e32 v14, v14
	s_nop 0
	v_mul_f32_e32 v14, v10, v14
	v_add_f32_e32 v10, v15, v71
	v_mul_f32_e32 v15, 0x3d372713, v10
	v_mul_f32_e32 v15, v10, v15
	v_fma_f32 v15, v10, v15, v10
	v_mul_f32_e32 v15, 0x3fcc422a, v15
	v_mul_f32_e32 v15, 0xbfb8aa3b, v15
	v_exp_f32_e32 v15, v15
	s_nop 0
	v_add_f32_e32 v15, 1.0, v15
	v_rcp_f32_e32 v15, v15
	s_nop 0
	v_mul_f32_e32 v10, v10, v15
	v_mul_f32_e32 v15, 0x3d372713, v11
	v_mul_f32_e32 v15, v11, v15
	v_fma_f32 v15, v11, v15, v11
	v_mul_f32_e32 v15, 0x3fcc422a, v15
	v_mul_f32_e32 v15, 0xbfb8aa3b, v15
	v_exp_f32_e32 v15, v15
	v_cvt_pk_bf16_f32 v9, v9, v10
	v_cvt_pk_bf16_f32 v10, v16, v13
	s_nop 0
	v_add_f32_e32 v15, 1.0, v15
	v_rcp_f32_e32 v15, v15
	s_nop 0
	v_mul_f32_e32 v11, v11, v15
	v_cvt_pk_bf16_f32 v11, v14, v11
	global_store_dwordx4 v[72:73], v[8:11], off offset:256 sc1
	s_nop 1
	v_mul_f32_e32 v8, 0x3d372713, v4
	v_mul_f32_e32 v8, v4, v8
	v_fma_f32 v8, v4, v8, v4
	v_mul_f32_e32 v8, 0x3fcc422a, v8
	v_mul_f32_e32 v8, 0xbfb8aa3b, v8
	v_exp_f32_e32 v8, v8
	s_nop 0
	v_add_f32_e32 v8, 1.0, v8
	v_rcp_f32_e32 v8, v8
	s_nop 0
	v_mul_f32_e32 v4, v4, v8
	v_mul_f32_e32 v8, 0x3d372713, v0
	v_mul_f32_e32 v8, v0, v8
	v_fma_f32 v8, v0, v8, v0
	v_mul_f32_e32 v8, 0x3fcc422a, v8
	v_mul_f32_e32 v8, 0xbfb8aa3b, v8
	v_exp_f32_e32 v8, v8
	s_nop 0
	v_add_f32_e32 v8, 1.0, v8
	v_rcp_f32_e32 v8, v8
	s_nop 0
	v_mul_f32_e32 v8, v0, v8
	v_add_f32_e32 v0, v5, v69
	v_mul_f32_e32 v5, 0x3d372713, v0
	v_mul_f32_e32 v5, v0, v5
	v_fma_f32 v5, v0, v5, v0
	v_mul_f32_e32 v5, 0x3fcc422a, v5
	v_mul_f32_e32 v5, 0xbfb8aa3b, v5
	v_exp_f32_e32 v5, v5
	s_nop 0
	v_add_f32_e32 v5, 1.0, v5
	v_rcp_f32_e32 v5, v5
	s_nop 0
	v_mul_f32_e32 v0, v0, v5
	v_mul_f32_e32 v5, 0x3d372713, v1
	v_mul_f32_e32 v5, v1, v5
	v_fma_f32 v5, v1, v5, v1
	v_mul_f32_e32 v5, 0x3fcc422a, v5
	v_mul_f32_e32 v5, 0xbfb8aa3b, v5
	v_exp_f32_e32 v5, v5
	v_cvt_pk_bf16_f32 v0, v4, v0
	s_nop 0
	v_add_f32_e32 v5, 1.0, v5
	v_rcp_f32_e32 v5, v5
	s_nop 0
	v_mul_f32_e32 v5, v1, v5
	v_add_f32_e32 v1, v6, v70
	v_mul_f32_e32 v6, 0x3d372713, v1
	v_mul_f32_e32 v6, v1, v6
	v_fma_f32 v6, v1, v6, v1
	v_mul_f32_e32 v6, 0x3fcc422a, v6
	v_mul_f32_e32 v6, 0xbfb8aa3b, v6
	v_exp_f32_e32 v6, v6
	s_nop 0
	v_add_f32_e32 v6, 1.0, v6
	v_rcp_f32_e32 v6, v6
	s_nop 0
	v_mul_f32_e32 v1, v1, v6
	v_mul_f32_e32 v6, 0x3d372713, v2
	v_mul_f32_e32 v6, v2, v6
	v_fma_f32 v6, v2, v6, v2
	v_mul_f32_e32 v6, 0x3fcc422a, v6
	v_mul_f32_e32 v6, 0xbfb8aa3b, v6
	v_exp_f32_e32 v6, v6
	s_nop 0
	v_add_f32_e32 v6, 1.0, v6
	v_rcp_f32_e32 v6, v6
	s_nop 0
	v_mul_f32_e32 v6, v2, v6
	v_add_f32_e32 v2, v7, v71
	v_mul_f32_e32 v7, 0x3d372713, v2
	v_mul_f32_e32 v7, v2, v7
	v_fma_f32 v7, v2, v7, v2
	v_mul_f32_e32 v7, 0x3fcc422a, v7
	v_mul_f32_e32 v7, 0xbfb8aa3b, v7
	v_exp_f32_e32 v7, v7
	s_nop 0
	v_add_f32_e32 v7, 1.0, v7
	v_rcp_f32_e32 v7, v7
	s_nop 0
	v_mul_f32_e32 v2, v2, v7
	v_mul_f32_e32 v7, 0x3d372713, v3
	v_mul_f32_e32 v7, v3, v7
	v_fma_f32 v7, v3, v7, v3
	v_mul_f32_e32 v7, 0x3fcc422a, v7
	v_mul_f32_e32 v7, 0xbfb8aa3b, v7
	v_exp_f32_e32 v7, v7
	v_cvt_pk_bf16_f32 v1, v1, v2
	v_cvt_pk_bf16_f32 v2, v8, v5
	s_nop 0
	v_add_f32_e32 v7, 1.0, v7
	v_rcp_f32_e32 v7, v7
	s_nop 0
	v_mul_f32_e32 v3, v3, v7
	v_cvt_pk_bf16_f32 v3, v6, v3
	global_store_dwordx4 v[74:75], v[0:3], off offset:256 sc1
	s_cbranch_vccnz .LBB0_551
	s_andn2_b64 vcc, exec, s[0:1]
	s_cbranch_vccnz .LBB0_550
	s_barrier
	s_branch .LBB0_550

; #define REIDS() do { tid = threadIdx.x; asm volatile("" : "+v"(tid)); lane = tid & 63; wave = __builtin_amdgcn_readfirstlane(tid >> 6); gw = blockIdx.x * 8 + wave; } while (0)
; __global__ void __launch_bounds__(NTHREADS, 2) fwd_kernel(Params P) {
;     ...
;     { pg8::Gemm gm{KV, CKW1, 8192, 256, 2048, 1024}; pg8::StaticOrder S; S.init(8192, 256, G, (int)blockIdx.x); EpiCmp E{H1K, CB}; pg8::gemm_phase<false>(lds, gm, S, E); }
;     { pg8::Gemm gm{KV + (size_t)MTOK * 256, CVW1, 8192, 256, 2048, 1024}; pg8::StaticOrder S; S.init(8192, 256, G, (int)((blockIdx.x + G - 32) % G)); EpiCmp E{H1V, CB + 256}; pg8::gemm_phase<false>(lds, gm, S, E); }
;     s5_phase(lds, USSM, S5A, S5B, P.in[13], P.in[14], P.in[15], YSSM, tid, lane, wave);
;     xcd_barrier(xbar); REIDS();
;     cmp2_phase(lds, H1K, H1V, P.in[20], P.in[22], KCMP, VCMPT, tid);
.LBB0_566:
	s_cmpk_gt_u32 s2, 63
	s_cbranch_scc1 .Lc1sig_done
	s_waitcnt vmcnt(0)
	s_barrier
	v_cmp_eq_u32_e32 vcc, 0, v154
	s_and_saveexec_b64 s[10:11], vcc
	s_cbranch_execz .Lc1sig_skip
	s_add_u32 s0, s30, 0x38998880
	s_addc_u32 s1, s31, 0
	v_mov_b32_e32 v0, 0
	v_mov_b32_e32 v1, 1
	global_atomic_add v0, v1, s[0:1]
	s_waitcnt vmcnt(0)
